# retention: ret_core units remapped so each XCD reads only states its own scan tasks wrote; ret_scan->ret_core waits only for the 32 workgroups of the XCD
# baseline (speedup 1.0000x reference)
.LBB0_1741:
	v_readlane_b32 s0, v253, 37
	v_readlane_b32 s16, v250, 0
	s_or_b32 s0, s0, 4
	v_readlane_b32 s19, v250, 3
	s_cmp_ge_i32 s0, s19
	v_readlane_b32 s17, v250, 1
	v_readlane_b32 s18, v250, 2
	s_cbranch_scc1 .LBB0_1797
	s_waitcnt vmcnt(0)
	v_readlane_b32 s2, v253, 40
	v_readlane_b32 s3, v253, 41
	s_and_b64 vcc, exec, s[2:3]
	s_waitcnt vmcnt(0)
	s_barrier
	s_cbranch_vccnz .LBB0_1796
	s_mov_b32 s2, -1
	s_nop 0
	v_mbcnt_lo_u32_b32 v0, s2, 0
	v_mbcnt_hi_u32_b32 v0, s2, v0
	s_nop 0
	v_cmp_eq_u32_e32 vcc, 0, v0
	s_and_saveexec_b64 s[16:17], vcc
	s_cbranch_execz .LBB0_1795
	s_cmp_lg_u32 s101, 1
	s_cbranch_scc1 .Lmy_gfull_9
	v_readlane_b32 s100, v253, 37
	v_readlane_b32 s3, v250, 7
	v_readlane_b32 s8, v250, 0
	v_readlane_b32 s9, v250, 1
	s_lshl_b32 s12, s100, 12
	s_add_i32 s12, s12, 0x9000
	s_and_b32 s13, s3, 63
	s_lshl_b32 s13, s13, 6
	s_add_i32 s2, s12, s13
	s_add_u32 s8, s8, 0x70000
	s_addc_u32 s9, s9, 0
	v_mov_b32_e32 v0, s2
	v_mov_b32_e32 v1, 1
	s_waitcnt vmcnt(0) lgkmcnt(0)
	global_atomic_add v0, v1, s[8:9]
	s_mov_b32 exec_lo, 0xff
	s_mov_b32 exec_hi, 0
	s_mov_b32 s2, -1
	v_mbcnt_lo_u32_b32 v0, s2, 0
	v_mbcnt_hi_u32_b32 v0, s2, v0
	v_lshlrev_b32_e32 v0, 9, v0
	s_and_b32 s13, s3, 7
	s_lshl_b32 s13, s13, 6
	s_add_i32 s13, s13, s12
	v_add_u32_e32 v0, s13, v0
	s_mov_b32 s100, 0
.Lmy_g9_spin:
	global_load_dword v2, v0, s[8:9] sc1
	s_waitcnt vmcnt(0)
	v_cmp_gt_u32_e32 vcc, 4, v2
	s_cmp_eq_u64 vcc, 0
	s_cbranch_scc1 .Lmy_g9_done
	s_sleep 1
	s_add_i32 s100, s100, 1
	s_cmp_lt_u32 s100, 0x4000
	s_cbranch_scc1 .Lmy_g9_spin
.Lmy_g9_done:
	s_mov_b64 exec, 1
	buffer_inv sc1
	s_waitcnt vmcnt(0)
	s_branch .LBB0_1795

.LBB0_1801:
	s_mov_b32 s98, s29
	s_cmp_lg_u32 s94, 0x100
	s_cbranch_scc1 .Lmy_coremap
	v_readlane_b32 s99, v250, 7
	s_and_b32 s98, s99, 7
	s_lshl_b32 s98, s98, 7
	s_lshr_b32 s99, s99, 3
	s_lshl_b32 s99, s99, 2
	s_add_i32 s98, s98, s99
	s_lshr_b32 s99, s29, 8
	s_add_i32 s98, s98, s99
.Lmy_coremap:
	s_ashr_i32 s2, s98, 6
	s_and_b32 s0, s98, 63
	s_and_b32 s7, s2, 7
	s_lshl_b32 s3, s98, 4
	s_and_b32 s3, s3, 0xffffe000
	s_lshl_b32 s8, s0, 7
	s_or_b32 s42, s3, s8
	s_lshl_b32 s3, s7, 2
	s_getpc_b64 s[8:9]
	s_add_u32 s8, s8, L2GAMMA@rel32@lo+4
	s_addc_u32 s9, s9, L2GAMMA@rel32@hi+12
	s_load_dword s9, s[8:9], s3 offset:0x0
	s_ashr_i32 s3, s2, 31
	s_lshl_b64 s[2:3], s[2:3], 24
	s_add_u32 s8, s23, s2
	v_add_u32_e32 v2, 0x200, v169
	v_add_u32_e32 v8, 0x400, v169
	v_add_u32_e32 v10, 0x600, v169
	s_addc_u32 s17, s26, s3
	s_lshl_b32 s34, s7, 9
	v_lshlrev_b32_e32 v0, 4, v169
	v_ashrrev_i32_e32 v33, 5, v169
	v_ashrrev_i32_e32 v36, 5, v2
	v_ashrrev_i32_e32 v38, 5, v8
	v_ashrrev_i32_e32 v40, 5, v10
	s_add_u32 s2, s12, s34
	v_and_b32_e32 v224, 0x1f0, v0
	v_add_u32_e32 v0, s42, v33
	v_add_u32_e32 v2, s42, v36
	v_add_u32_e32 v8, s42, v38
	v_add_u32_e32 v10, s42, v40
	v_add_u32_e32 v16, 0x800, v169
	v_add_u32_e32 v18, 0xa00, v169
	s_addc_u32 s3, s13, 0
	v_ashrrev_i32_e32 v1, 31, v0
	v_ashrrev_i32_e32 v3, 31, v2
	v_ashrrev_i32_e32 v9, 31, v8
	v_ashrrev_i32_e32 v11, 31, v10
	v_ashrrev_i32_e32 v42, 5, v16
	v_ashrrev_i32_e32 v43, 5, v18
	v_add_u32_e32 v24, 0xc00, v169
	v_lshl_add_u64 v[28:29], s[2:3], 0, v[224:225]
	v_lshlrev_b64 v[0:1], 12, v[0:1]
	v_lshlrev_b64 v[2:3], 12, v[2:3]
	v_lshlrev_b64 v[8:9], 12, v[8:9]
	v_lshlrev_b64 v[10:11], 12, v[10:11]
	v_add_u32_e32 v16, s42, v42
	v_add_u32_e32 v18, s42, v43
	v_ashrrev_i32_e32 v44, 5, v24
	v_add_u32_e32 v30, 0xe00, v169
	v_lshl_add_u64 v[0:1], v[28:29], 0, v[0:1]
	v_lshl_add_u64 v[4:5], v[28:29], 0, v[2:3]
	v_lshl_add_u64 v[8:9], v[28:29], 0, v[8:9]
	v_lshl_add_u64 v[12:13], v[28:29], 0, v[10:11]
	v_ashrrev_i32_e32 v17, 31, v16
	v_ashrrev_i32_e32 v19, 31, v18
	v_add_u32_e32 v24, s42, v44
	v_ashrrev_i32_e32 v45, 5, v30
	s_waitcnt vmcnt(0) lgkmcnt(0)
	s_barrier
	global_load_dwordx4 v[0:3], v[0:1], off
	s_nop 0
	global_load_dwordx4 v[4:7], v[4:5], off
	s_nop 0
	global_load_dwordx4 v[8:11], v[8:9], off
	s_nop 0
	global_load_dwordx4 v[12:15], v[12:13], off
	v_lshlrev_b64 v[16:17], 12, v[16:17]
	v_lshlrev_b64 v[18:19], 12, v[18:19]
	v_ashrrev_i32_e32 v25, 31, v24
	v_add_u32_e32 v30, s42, v45
	v_lshl_add_u64 v[16:17], v[28:29], 0, v[16:17]
	v_lshl_add_u64 v[20:21], v[28:29], 0, v[18:19]
	v_lshlrev_b64 v[24:25], 12, v[24:25]
	v_ashrrev_i32_e32 v31, 31, v30
	global_load_dwordx4 v[16:19], v[16:17], off
	s_nop 0
	global_load_dwordx4 v[20:23], v[20:21], off
	v_lshl_add_u64 v[24:25], v[28:29], 0, v[24:25]
	v_lshlrev_b64 v[30:31], 12, v[30:31]
	global_load_dwordx4 v[24:27], v[24:25], off
	v_lshl_add_u64 v[28:29], v[28:29], 0, v[30:31]
	global_load_dwordx4 v[28:31], v[28:29], off
	v_add_u32_e32 v32, 0, v224
	s_movk_i32 s7, 0x210
	v_mad_u64_u32 v[34:35], s[2:3], v33, s7, v[32:33]
	v_mad_u64_u32 v[36:37], s[2:3], v36, s7, v[32:33]
	v_mad_u64_u32 v[38:39], s[2:3], v38, s7, v[32:33]
	v_mad_u64_u32 v[40:41], s[2:3], v40, s7, v[32:33]
	s_lshl_b32 s0, s0, 18
	s_add_u32 s16, s8, s0
	s_addc_u32 s17, s17, 0
	s_lshl_b32 s0, s18, 1
	s_or_b32 s0, s0, 1
	v_readlane_b32 s30, v252, 42
	s_add_i32 s8, 0, 0x14800
	s_waitcnt vmcnt(7)
	ds_write_b128 v34, v[0:3]
	s_waitcnt vmcnt(6)
	ds_write_b128 v36, v[4:7]
	s_waitcnt vmcnt(5)
	ds_write_b128 v38, v[8:11]
	s_waitcnt vmcnt(4)
	ds_write_b128 v40, v[12:15]
	v_mad_u64_u32 v[0:1], s[2:3], v42, s7, v[32:33]
	v_bfe_u32 v4, v169, 2, 4
	v_lshl_or_b32 v2, s18, 5, v4
	v_ashrrev_i32_e32 v3, 31, v2
	v_lshl_or_b32 v4, s0, 4, v4
	v_lshlrev_b64 v[2:3], 9, v[2:3]
	s_waitcnt vmcnt(3)
	ds_write_b128 v0, v[16:19]
	v_mad_u64_u32 v[0:1], s[2:3], v43, s7, v[32:33]
	s_waitcnt vmcnt(2)
	ds_write_b128 v0, v[20:23]
	v_mad_u64_u32 v[0:1], s[2:3], v44, s7, v[32:33]
	s_waitcnt vmcnt(1)
	ds_write_b128 v0, v[24:27]
	v_mad_u64_u32 v[0:1], s[2:3], v45, s7, v[32:33]
	s_waitcnt vmcnt(0)
	ds_write_b128 v0, v[28:31]
	v_lshrrev_b32_e32 v0, 4, v169
	v_xor_b32_e32 v0, v0, v169
	v_lshlrev_b32_e32 v0, 4, v0
	v_and_b32_e32 v224, 48, v0
	v_lshl_add_u64 v[0:1], s[16:17], 0, v[224:225]
	s_lshl_b32 s2, s18, 11
	v_ashrrev_i32_e32 v5, 31, v4
	s_waitcnt vmcnt(0) lgkmcnt(0)
	v_lshl_add_u64 v[2:3], v[0:1], 0, v[2:3]
	s_add_i32 m0, s30, s2
	v_lshlrev_b64 v[4:5], 9, v[4:5]
	s_lshl_b32 s0, s0, 10
	global_load_lds_dwordx4 v[2:3], off
	v_lshl_add_u64 v[0:1], v[0:1], 0, v[4:5]
	s_add_i32 m0, s30, s0
	v_lshl_add_u64 v[4:5], v[2:3], 0, 64
	global_load_lds_dwordx4 v[0:1], off
	s_add_i32 m0, s8, s2
	v_readlane_b32 s31, v252, 43
	global_load_lds_dwordx4 v[4:5], off
	v_lshl_add_u64 v[4:5], v[0:1], 0, 64
	s_add_i32 m0, s8, s0
	s_mov_b64 s[46:47], 0xc0
	global_load_lds_dwordx4 v[4:5], off
	v_lshl_add_u64 v[4:5], v[2:3], 0, s[24:25]
	s_add_i32 m0, s31, s2
	v_readlane_b32 s33, v252, 44
	global_load_lds_dwordx4 v[4:5], off
	v_lshl_add_u64 v[4:5], v[0:1], 0, s[24:25]
	s_add_i32 m0, s31, s0
	v_lshl_add_u64 v[2:3], v[2:3], 0, s[46:47]
	global_load_lds_dwordx4 v[4:5], off
	s_add_i32 m0, s33, s2
	v_lshl_add_u64 v[0:1], v[0:1], 0, s[46:47]
	global_load_lds_dwordx4 v[2:3], off
	s_add_i32 m0, s33, s0
	s_mov_b64 s[38:39], 0x100
	global_load_lds_dwordx4 v[0:1], off
	v_mov_b32 v12, 0
	v_mov_b32 v13, 0
	v_mov_b32 v14, 0
	v_mov_b32 v15, 0
	v_mov_b32 v8, 0
	v_mov_b32 v9, 0
	v_mov_b32 v10, 0
	v_mov_b32 v11, 0
	v_mov_b32 v4, 0
	v_mov_b32 v5, 0
	v_mov_b32 v6, 0
	v_mov_b32 v7, 0
	v_mov_b32 v0, 0
	v_mov_b32 v1, 0
	v_mov_b32 v2, 0
	v_mov_b32 v3, 0
	v_mov_b32 v68, 0
	v_mov_b32 v69, 0
	v_mov_b32 v70, 0
	v_mov_b32 v71, 0
	v_mov_b32 v64, 0
	v_mov_b32 v65, 0
	v_mov_b32 v66, 0
	v_mov_b32 v67, 0
	v_mov_b32 v60, 0
	v_mov_b32 v61, 0
	v_mov_b32 v62, 0
	v_mov_b32 v63, 0
	v_mov_b32 v56, 0
	v_mov_b32 v57, 0
	v_mov_b32 v58, 0
	v_mov_b32 v59, 0
	v_mov_b32 v16, 0
	v_mov_b32 v17, 0
	v_mov_b32 v18, 0
	v_mov_b32 v19, 0
	v_mov_b32 v20, 0
	v_mov_b32 v21, 0
	v_mov_b32 v22, 0
	v_mov_b32 v23, 0
	v_mov_b32 v24, 0
	v_mov_b32 v25, 0
	v_mov_b32 v26, 0
	v_mov_b32 v27, 0
	v_mov_b32 v28, 0
	v_mov_b32 v29, 0
	v_mov_b32 v30, 0
	v_mov_b32 v31, 0
	v_mov_b32 v84, 0
	v_mov_b32 v85, 0
	v_mov_b32 v86, 0
	v_mov_b32 v87, 0
	v_mov_b32 v80, 0
	v_mov_b32 v81, 0
	v_mov_b32 v82, 0
	v_mov_b32 v83, 0
	v_mov_b32 v76, 0
	v_mov_b32 v77, 0
	v_mov_b32 v78, 0
	v_mov_b32 v79, 0
	v_mov_b32 v72, 0
	v_mov_b32 v73, 0
	v_mov_b32 v74, 0
	v_mov_b32 v75, 0
	v_mov_b32 v32, 0
	v_mov_b32 v33, 0
	v_mov_b32 v34, 0
	v_mov_b32 v35, 0
	v_mov_b32 v36, 0
	v_mov_b32 v37, 0
	v_mov_b32 v38, 0
	v_mov_b32 v39, 0
	v_mov_b32 v40, 0
	v_mov_b32 v41, 0
	v_mov_b32 v42, 0
	v_mov_b32 v43, 0
	v_mov_b32 v44, 0
	v_mov_b32 v45, 0
	v_mov_b32 v46, 0
	v_mov_b32 v47, 0
	v_mov_b32 v100, 0
	v_mov_b32 v101, 0
	v_mov_b32 v102, 0
	v_mov_b32 v103, 0
	v_mov_b32 v96, 0
	v_mov_b32 v97, 0
	v_mov_b32 v98, 0
	v_mov_b32 v99, 0
	v_mov_b32 v92, 0
	v_mov_b32 v93, 0
	v_mov_b32 v94, 0
	v_mov_b32 v95, 0
	v_mov_b32 v88, 0
	v_mov_b32 v89, 0
	v_mov_b32 v90, 0
	v_mov_b32 v91, 0
	v_mov_b32 v48, 0
	v_mov_b32 v49, 0
	v_mov_b32 v50, 0
	v_mov_b32 v51, 0
	v_mov_b32 v52, 0
	v_mov_b32 v53, 0
	v_mov_b32 v54, 0
	v_mov_b32 v55, 0
	v_mov_b32 v116, 0
	v_mov_b32 v117, 0
	v_mov_b32 v118, 0
	v_mov_b32 v119, 0
	v_mov_b32 v120, 0
	v_mov_b32 v121, 0
	v_mov_b32 v122, 0
	v_mov_b32 v123, 0
	v_mov_b32 v124, 0
	v_mov_b32 v125, 0
	v_mov_b32 v126, 0
	v_mov_b32 v127, 0
	v_mov_b32 v112, 0
	v_mov_b32 v113, 0
	v_mov_b32 v114, 0
	v_mov_b32 v115, 0
	v_mov_b32 v108, 0
	v_mov_b32 v109, 0
	v_mov_b32 v110, 0
	v_mov_b32 v111, 0
	v_mov_b32 v104, 0
	v_mov_b32 v105, 0
	v_mov_b32 v106, 0
	v_mov_b32 v107, 0
	s_waitcnt vmcnt(6) lgkmcnt(0)
	s_barrier
	s_lshl_b32 s0, s18, 4
	v_and_b32_e32 v128, 15, v169
	s_and_b32 s0, s0, 0xfffffc0
	v_or_b32_e32 v132, s0, v128
	v_lshrrev_b32_e32 v152, 4, v169
	s_lshl_b32 s0, s18, 6
	v_lshrrev_b32_e32 v129, 2, v169
	s_and_b32 s0, s0, 0xc0
	v_xor_b32_e32 v129, v152, v129
	v_or_b32_e32 v128, s0, v128
	v_lshlrev_b32_e32 v129, 4, v129
	v_and_b32_e32 v129, 48, v129
	v_lshlrev_b32_e32 v128, 6, v128
	v_add3_u32 v153, s30, v129, v128
	ds_read_b128 v[128:131], v153
	v_and_b32_e32 v133, 48, v169
	v_mul_lo_u32 v132, v132, s7
	v_add3_u32 v148, 0, v133, v132
	ds_read_b128 v[132:135], v148
	ds_read_b128 v[136:139], v148 offset:8448
	ds_read_b128 v[140:143], v153 offset:1024
	ds_read_b128 v[144:147], v148 offset:16896
	ds_read_b128 v[148:151], v148 offset:25344
	s_waitcnt lgkmcnt(0)
	v_mfma_f32_16x16x32_f16 v[12:15], v[128:131], v[132:135], v[12:15]
	s_lshl_b32 s0, s18, 1
	s_lshl_b32 s2, s18, 11
	v_readlane_b32 s35, v252, 45
	v_mfma_f32_16x16x32_f16 v[16:19], v[128:131], v[136:139], v[16:19]
	s_add_i32 m0, s35, s2
	s_or_b32 s0, s0, 1
	s_mov_b64 s[48:49], 0x140
	v_mfma_f32_16x16x32_f16 v[32:35], v[128:131], v[144:147], v[32:35]
	s_mov_b64 s[44:45], 0x180
	s_mov_b64 s[50:51], 0x1c0
	v_mfma_f32_16x16x32_f16 v[48:51], v[128:131], v[148:151], v[48:51]
	v_mfma_f32_16x16x32_f16 v[8:11], v[140:143], v[132:135], v[8:11]
	v_mfma_f32_16x16x32_f16 v[20:23], v[140:143], v[136:139], v[20:23]
	v_mfma_f32_16x16x32_f16 v[36:39], v[140:143], v[144:147], v[36:39]
	v_mfma_f32_16x16x32_f16 v[52:55], v[140:143], v[148:151], v[52:55]
	ds_read_b128 v[128:131], v153 offset:2048
	ds_read_b128 v[140:143], v153 offset:3072
	s_waitcnt lgkmcnt(0)
	v_mfma_f32_16x16x32_f16 v[4:7], v[128:131], v[132:135], v[4:7]
	v_mfma_f32_16x16x32_f16 v[24:27], v[128:131], v[136:139], v[24:27]
	v_mfma_f32_16x16x32_f16 v[40:43], v[128:131], v[144:147], v[40:43]
	v_mfma_f32_16x16x32_f16 v[116:119], v[128:131], v[148:151], v[116:119]
	v_xor_b32_e32 v128, v152, v169
	v_lshlrev_b32_e32 v128, 4, v128
	v_and_b32_e32 v224, 48, v128
	v_mfma_f32_16x16x32_f16 v[0:3], v[140:143], v[132:135], v[0:3]
	v_bfe_u32 v132, v169, 2, 4
	v_lshl_or_b32 v130, s18, 5, v132
	v_ashrrev_i32_e32 v131, 31, v130
	v_lshl_add_u64 v[128:129], s[16:17], 0, v[224:225]
	v_lshlrev_b64 v[130:131], 9, v[130:131]
	v_lshl_add_u64 v[130:131], v[128:129], 0, v[130:131]
	v_lshl_add_u64 v[130:131], v[130:131], 0, s[38:39]
	global_load_lds_dwordx4 v[130:131], off
	v_lshl_or_b32 v130, s0, 4, v132
	v_ashrrev_i32_e32 v131, 31, v130
	v_lshlrev_b64 v[130:131], 9, v[130:131]
	v_lshl_add_u64 v[128:129], v[128:129], 0, v[130:131]
	s_lshl_b32 s0, s0, 10
	v_lshl_add_u64 v[128:129], v[128:129], 0, s[38:39]
	s_add_i32 m0, s35, s0
	v_mfma_f32_16x16x32_f16 v[120:123], v[140:143], v[148:151], v[120:123]
	global_load_lds_dwordx4 v[128:129], off
	s_waitcnt vmcnt(6) lgkmcnt(0)
	s_barrier
	s_lshl_b32 s0, s18, 4
	v_and_b32_e32 v128, 15, v169
	s_and_b32 s0, s0, 0xfffffc0
	v_or_b32_e32 v132, s0, v128
	v_lshrrev_b32_e32 v152, 4, v169
	s_lshl_b32 s0, s18, 6
	v_lshrrev_b32_e32 v129, 2, v169
	s_and_b32 s0, s0, 0xc0
	v_xor_b32_e32 v129, v152, v129
	v_or_b32_e32 v128, s0, v128
	v_lshlrev_b32_e32 v129, 4, v129
	v_and_b32_e32 v129, 48, v129
	v_lshlrev_b32_e32 v128, 6, v128
	v_add3_u32 v153, s8, v129, v128
	ds_read_b128 v[128:131], v153
	v_and_b32_e32 v133, 48, v169
	v_mul_lo_u32 v132, v132, s7
	v_add3_u32 v148, 0, v133, v132
	v_mfma_f32_16x16x32_f16 v[28:31], v[140:143], v[136:139], v[28:31]
	s_lshl_b32 s0, s18, 1
	s_lshl_b32 s2, s18, 11
	s_add_i32 m0, s30, s2
	v_mfma_f32_16x16x32_f16 v[44:47], v[140:143], v[144:147], v[44:47]
	ds_read_b128 v[132:135], v148 offset:64
	ds_read_b128 v[136:139], v148 offset:8512
	ds_read_b128 v[140:143], v153 offset:1024
	ds_read_b128 v[144:147], v148 offset:16960
	ds_read_b128 v[148:151], v148 offset:25408
	s_or_b32 s0, s0, 1
	s_waitcnt lgkmcnt(0)
	v_mfma_f32_16x16x32_f16 v[12:15], v[128:131], v[132:135], v[12:15]
	v_mfma_f32_16x16x32_f16 v[16:19], v[128:131], v[136:139], v[16:19]
	v_mfma_f32_16x16x32_f16 v[32:35], v[128:131], v[144:147], v[32:35]
	v_mfma_f32_16x16x32_f16 v[48:51], v[128:131], v[148:151], v[48:51]
	v_mfma_f32_16x16x32_f16 v[8:11], v[140:143], v[132:135], v[8:11]
	v_mfma_f32_16x16x32_f16 v[20:23], v[140:143], v[136:139], v[20:23]
	v_mfma_f32_16x16x32_f16 v[36:39], v[140:143], v[144:147], v[36:39]
	v_mfma_f32_16x16x32_f16 v[52:55], v[140:143], v[148:151], v[52:55]
	ds_read_b128 v[128:131], v153 offset:2048
	ds_read_b128 v[140:143], v153 offset:3072
	s_waitcnt lgkmcnt(0)
	v_mfma_f32_16x16x32_f16 v[4:7], v[128:131], v[132:135], v[4:7]
	v_mfma_f32_16x16x32_f16 v[24:27], v[128:131], v[136:139], v[24:27]
	v_mfma_f32_16x16x32_f16 v[40:43], v[128:131], v[144:147], v[40:43]
	v_mfma_f32_16x16x32_f16 v[116:119], v[128:131], v[148:151], v[116:119]
	v_xor_b32_e32 v128, v152, v169
	v_lshlrev_b32_e32 v128, 4, v128
	v_and_b32_e32 v224, 48, v128
	v_mfma_f32_16x16x32_f16 v[0:3], v[140:143], v[132:135], v[0:3]
	v_bfe_u32 v132, v169, 2, 4
	v_lshl_or_b32 v130, s18, 5, v132
	v_ashrrev_i32_e32 v131, 31, v130
	v_lshl_add_u64 v[128:129], s[16:17], 0, v[224:225]
	v_lshlrev_b64 v[130:131], 9, v[130:131]
	v_lshl_add_u64 v[130:131], v[128:129], 0, v[130:131]
	v_lshl_add_u64 v[130:131], v[130:131], 0, s[48:49]
	global_load_lds_dwordx4 v[130:131], off
	v_lshl_or_b32 v130, s0, 4, v132
	v_ashrrev_i32_e32 v131, 31, v130
	v_lshlrev_b64 v[130:131], 9, v[130:131]
	v_lshl_add_u64 v[128:129], v[128:129], 0, v[130:131]
	s_lshl_b32 s0, s0, 10
	v_lshl_add_u64 v[128:129], v[128:129], 0, s[48:49]
	s_add_i32 m0, s30, s0
	v_mfma_f32_16x16x32_f16 v[120:123], v[140:143], v[148:151], v[120:123]
	global_load_lds_dwordx4 v[128:129], off
	s_waitcnt vmcnt(6) lgkmcnt(0)
	s_barrier
	s_lshl_b32 s0, s18, 4
	v_and_b32_e32 v128, 15, v169
	s_and_b32 s0, s0, 0xfffffc0
	v_or_b32_e32 v132, s0, v128
	v_lshrrev_b32_e32 v152, 4, v169
	s_lshl_b32 s0, s18, 6
	v_lshrrev_b32_e32 v129, 2, v169
	s_and_b32 s0, s0, 0xc0
	v_xor_b32_e32 v129, v152, v129
	v_or_b32_e32 v128, s0, v128
	v_lshlrev_b32_e32 v129, 4, v129
	v_and_b32_e32 v129, 48, v129
	v_lshlrev_b32_e32 v128, 6, v128
	v_add3_u32 v153, s31, v129, v128
	ds_read_b128 v[128:131], v153
	v_and_b32_e32 v133, 48, v169
	v_mul_lo_u32 v132, v132, s7
	v_add3_u32 v148, 0, v133, v132
	v_mfma_f32_16x16x32_f16 v[28:31], v[140:143], v[136:139], v[28:31]
	s_lshl_b32 s0, s18, 1
	s_lshl_b32 s2, s18, 11
	s_add_i32 m0, s8, s2
	v_mfma_f32_16x16x32_f16 v[44:47], v[140:143], v[144:147], v[44:47]
	ds_read_b128 v[132:135], v148 offset:128
	ds_read_b128 v[136:139], v148 offset:8576
	ds_read_b128 v[140:143], v153 offset:1024
	ds_read_b128 v[144:147], v148 offset:17024
	ds_read_b128 v[148:151], v148 offset:25472
	s_or_b32 s0, s0, 1
	s_waitcnt lgkmcnt(0)
	v_mfma_f32_16x16x32_f16 v[12:15], v[128:131], v[132:135], v[12:15]
	v_mfma_f32_16x16x32_f16 v[16:19], v[128:131], v[136:139], v[16:19]
	v_mfma_f32_16x16x32_f16 v[32:35], v[128:131], v[144:147], v[32:35]
	v_mfma_f32_16x16x32_f16 v[48:51], v[128:131], v[148:151], v[48:51]
	v_mfma_f32_16x16x32_f16 v[8:11], v[140:143], v[132:135], v[8:11]
	v_mfma_f32_16x16x32_f16 v[20:23], v[140:143], v[136:139], v[20:23]
	v_mfma_f32_16x16x32_f16 v[36:39], v[140:143], v[144:147], v[36:39]
	v_mfma_f32_16x16x32_f16 v[52:55], v[140:143], v[148:151], v[52:55]
	ds_read_b128 v[128:131], v153 offset:2048
	ds_read_b128 v[140:143], v153 offset:3072
	s_waitcnt lgkmcnt(0)
	v_mfma_f32_16x16x32_f16 v[4:7], v[128:131], v[132:135], v[4:7]
	v_mfma_f32_16x16x32_f16 v[24:27], v[128:131], v[136:139], v[24:27]
	v_mfma_f32_16x16x32_f16 v[40:43], v[128:131], v[144:147], v[40:43]
	v_mfma_f32_16x16x32_f16 v[116:119], v[128:131], v[148:151], v[116:119]
	v_xor_b32_e32 v128, v152, v169
	v_lshlrev_b32_e32 v128, 4, v128
	v_and_b32_e32 v224, 48, v128
	v_mfma_f32_16x16x32_f16 v[0:3], v[140:143], v[132:135], v[0:3]
	v_bfe_u32 v132, v169, 2, 4
	v_lshl_or_b32 v130, s18, 5, v132
	v_ashrrev_i32_e32 v131, 31, v130
	v_lshl_add_u64 v[128:129], s[16:17], 0, v[224:225]
	v_lshlrev_b64 v[130:131], 9, v[130:131]
	v_lshl_add_u64 v[130:131], v[128:129], 0, v[130:131]
	v_lshl_add_u64 v[130:131], v[130:131], 0, s[44:45]
	global_load_lds_dwordx4 v[130:131], off
	v_lshl_or_b32 v130, s0, 4, v132
	v_ashrrev_i32_e32 v131, 31, v130
	v_lshlrev_b64 v[130:131], 9, v[130:131]
	v_lshl_add_u64 v[128:129], v[128:129], 0, v[130:131]
	s_lshl_b32 s0, s0, 10
	v_lshl_add_u64 v[128:129], v[128:129], 0, s[44:45]
	s_add_i32 m0, s8, s0
	v_mfma_f32_16x16x32_f16 v[120:123], v[140:143], v[148:151], v[120:123]
	global_load_lds_dwordx4 v[128:129], off
	s_waitcnt vmcnt(6) lgkmcnt(0)
	s_barrier
	s_lshl_b32 s0, s18, 4
	v_and_b32_e32 v128, 15, v169
	s_and_b32 s0, s0, 0xfffffc0
	v_or_b32_e32 v132, s0, v128
	v_lshrrev_b32_e32 v152, 4, v169
	s_lshl_b32 s0, s18, 6
	v_lshrrev_b32_e32 v129, 2, v169
	s_and_b32 s0, s0, 0xc0
	v_xor_b32_e32 v129, v152, v129
	v_or_b32_e32 v128, s0, v128
	v_lshlrev_b32_e32 v129, 4, v129
	v_and_b32_e32 v129, 48, v129
	v_lshlrev_b32_e32 v128, 6, v128
	v_add3_u32 v153, s33, v129, v128
	ds_read_b128 v[128:131], v153
	v_and_b32_e32 v133, 48, v169
	v_mul_lo_u32 v132, v132, s7
	v_add3_u32 v148, 0, v133, v132
	v_mfma_f32_16x16x32_f16 v[28:31], v[140:143], v[136:139], v[28:31]
	s_lshl_b32 s0, s18, 1
	s_lshl_b32 s2, s18, 11
	s_add_i32 m0, s31, s2
	v_mfma_f32_16x16x32_f16 v[44:47], v[140:143], v[144:147], v[44:47]
	ds_read_b128 v[132:135], v148 offset:192
	ds_read_b128 v[136:139], v148 offset:8640
	ds_read_b128 v[140:143], v153 offset:1024
	ds_read_b128 v[144:147], v148 offset:17088
	ds_read_b128 v[148:151], v148 offset:25536
	s_or_b32 s0, s0, 1
	s_waitcnt lgkmcnt(0)
	v_mfma_f32_16x16x32_f16 v[12:15], v[128:131], v[132:135], v[12:15]
	v_mfma_f32_16x16x32_f16 v[16:19], v[128:131], v[136:139], v[16:19]
	v_mfma_f32_16x16x32_f16 v[32:35], v[128:131], v[144:147], v[32:35]
	v_mfma_f32_16x16x32_f16 v[48:51], v[128:131], v[148:151], v[48:51]
	v_mfma_f32_16x16x32_f16 v[8:11], v[140:143], v[132:135], v[8:11]
	v_mfma_f32_16x16x32_f16 v[20:23], v[140:143], v[136:139], v[20:23]
	v_mfma_f32_16x16x32_f16 v[36:39], v[140:143], v[144:147], v[36:39]
	v_mfma_f32_16x16x32_f16 v[52:55], v[140:143], v[148:151], v[52:55]
	ds_read_b128 v[128:131], v153 offset:2048
	ds_read_b128 v[140:143], v153 offset:3072
	s_waitcnt lgkmcnt(0)
	v_mfma_f32_16x16x32_f16 v[4:7], v[128:131], v[132:135], v[4:7]
	v_mfma_f32_16x16x32_f16 v[24:27], v[128:131], v[136:139], v[24:27]
	v_mfma_f32_16x16x32_f16 v[40:43], v[128:131], v[144:147], v[40:43]
	v_mfma_f32_16x16x32_f16 v[116:119], v[128:131], v[148:151], v[116:119]
	v_xor_b32_e32 v128, v152, v169
	v_lshlrev_b32_e32 v128, 4, v128
	v_and_b32_e32 v224, 48, v128
	v_mfma_f32_16x16x32_f16 v[0:3], v[140:143], v[132:135], v[0:3]
	v_bfe_u32 v132, v169, 2, 4
	v_lshl_or_b32 v130, s18, 5, v132
	v_ashrrev_i32_e32 v131, 31, v130
	v_lshl_add_u64 v[128:129], s[16:17], 0, v[224:225]
	v_lshlrev_b64 v[130:131], 9, v[130:131]
	v_lshl_add_u64 v[130:131], v[128:129], 0, v[130:131]
	v_lshl_add_u64 v[130:131], v[130:131], 0, s[50:51]
	global_load_lds_dwordx4 v[130:131], off
	v_lshl_or_b32 v130, s0, 4, v132
	v_ashrrev_i32_e32 v131, 31, v130
	v_lshlrev_b64 v[130:131], 9, v[130:131]
	v_lshl_add_u64 v[128:129], v[128:129], 0, v[130:131]
	s_lshl_b32 s0, s0, 10
	v_lshl_add_u64 v[128:129], v[128:129], 0, s[50:51]
	s_add_i32 m0, s31, s0
	v_mfma_f32_16x16x32_f16 v[120:123], v[140:143], v[148:151], v[120:123]
	global_load_lds_dwordx4 v[128:129], off
	s_waitcnt vmcnt(6) lgkmcnt(0)
	s_barrier
	s_lshl_b32 s0, s18, 4
	v_and_b32_e32 v128, 15, v169
	s_and_b32 s0, s0, 0xfffffc0
	v_or_b32_e32 v132, s0, v128
	v_lshrrev_b32_e32 v152, 4, v169
	s_lshl_b32 s0, s18, 6
	v_lshrrev_b32_e32 v153, 2, v169
	s_and_b32 s0, s0, 0xc0
	v_xor_b32_e32 v129, v152, v153
	v_or_b32_e32 v128, s0, v128
	v_lshlrev_b32_e32 v129, 4, v129
	v_and_b32_e32 v129, 48, v129
	v_lshlrev_b32_e32 v128, 6, v128
	v_add3_u32 v154, s35, v129, v128
	ds_read_b128 v[128:131], v154
	v_and_b32_e32 v133, 48, v169
	v_mul_lo_u32 v132, v132, s7
	v_add3_u32 v148, 0, v133, v132
	v_mfma_f32_16x16x32_f16 v[28:31], v[140:143], v[136:139], v[28:31]
	s_lshl_b32 s0, s18, 1
	s_lshl_b32 s2, s18, 11
	s_add_i32 m0, s33, s2
	v_mfma_f32_16x16x32_f16 v[44:47], v[140:143], v[144:147], v[44:47]
	ds_read_b128 v[132:135], v148 offset:256
	ds_read_b128 v[136:139], v148 offset:8704
	ds_read_b128 v[140:143], v154 offset:1024
	ds_read_b128 v[144:147], v148 offset:17152
	ds_read_b128 v[148:151], v148 offset:25600
	s_or_b32 s0, s0, 1
	s_waitcnt lgkmcnt(0)
	v_mfma_f32_16x16x32_f16 v[12:15], v[128:131], v[132:135], v[12:15]
	v_mfma_f32_16x16x32_f16 v[16:19], v[128:131], v[136:139], v[16:19]
	v_mfma_f32_16x16x32_f16 v[32:35], v[128:131], v[144:147], v[32:35]
	v_mfma_f32_16x16x32_f16 v[48:51], v[128:131], v[148:151], v[48:51]
	v_mfma_f32_16x16x32_f16 v[8:11], v[140:143], v[132:135], v[8:11]
	v_mfma_f32_16x16x32_f16 v[20:23], v[140:143], v[136:139], v[20:23]
	v_mfma_f32_16x16x32_f16 v[36:39], v[140:143], v[144:147], v[36:39]
	v_mfma_f32_16x16x32_f16 v[52:55], v[140:143], v[148:151], v[52:55]
	ds_read_b128 v[128:131], v154 offset:2048
	ds_read_b128 v[140:143], v154 offset:3072
	s_waitcnt lgkmcnt(0)
	v_mfma_f32_16x16x32_f16 v[4:7], v[128:131], v[132:135], v[4:7]
	v_mfma_f32_16x16x32_f16 v[24:27], v[128:131], v[136:139], v[24:27]
	v_mfma_f32_16x16x32_f16 v[40:43], v[128:131], v[144:147], v[40:43]
	v_mfma_f32_16x16x32_f16 v[116:119], v[128:131], v[148:151], v[116:119]
	v_xor_b32_e32 v128, v152, v169
	v_lshlrev_b32_e32 v128, 4, v128
	v_and_b32_e32 v224, 48, v128
	v_mfma_f32_16x16x32_f16 v[0:3], v[140:143], v[132:135], v[0:3]
	v_and_or_b32 v132, v153, 15, v246
	v_lshl_add_u32 v130, s18, 5, v132
	v_ashrrev_i32_e32 v131, 31, v130
	v_lshl_add_u64 v[128:129], s[16:17], 0, v[224:225]
	v_lshlrev_b64 v[130:131], 9, v[130:131]
	v_lshl_add_u64 v[130:131], v[128:129], 0, v[130:131]
	global_load_lds_dwordx4 v[130:131], off
	v_lshl_add_u32 v130, s0, 4, v132
	v_ashrrev_i32_e32 v131, 31, v130
	v_lshlrev_b64 v[130:131], 9, v[130:131]
	s_lshl_b32 s0, s0, 10
	v_lshl_add_u64 v[128:129], v[128:129], 0, v[130:131]
	s_add_i32 m0, s33, s0
	v_mfma_f32_16x16x32_f16 v[120:123], v[140:143], v[148:151], v[120:123]
	global_load_lds_dwordx4 v[128:129], off
	s_waitcnt vmcnt(6) lgkmcnt(0)
	s_barrier
	s_lshl_b32 s0, s18, 4
	v_and_b32_e32 v128, 15, v169
	s_and_b32 s0, s0, 0xfffffc0
	v_or_b32_e32 v132, s0, v128
	v_lshrrev_b32_e32 v152, 4, v169
	s_lshl_b32 s0, s18, 6
	v_lshrrev_b32_e32 v153, 2, v169
	s_and_b32 s0, s0, 0xc0
	v_xor_b32_e32 v129, v152, v153
	v_or_b32_e32 v128, s0, v128
	v_lshlrev_b32_e32 v129, 4, v129
	v_and_b32_e32 v129, 48, v129
	v_lshlrev_b32_e32 v128, 6, v128
	v_add3_u32 v154, s30, v129, v128
	ds_read_b128 v[128:131], v154
	v_and_b32_e32 v133, 48, v169
	v_mul_lo_u32 v132, v132, s7
	v_add3_u32 v148, 0, v133, v132
	v_mfma_f32_16x16x32_f16 v[28:31], v[140:143], v[136:139], v[28:31]
	s_lshl_b32 s0, s18, 1
	s_lshl_b32 s2, s18, 11
	s_add_i32 m0, s35, s2
	v_mfma_f32_16x16x32_f16 v[44:47], v[140:143], v[144:147], v[44:47]
	ds_read_b128 v[132:135], v148 offset:320
	ds_read_b128 v[136:139], v148 offset:8768
	ds_read_b128 v[140:143], v154 offset:1024
	ds_read_b128 v[144:147], v148 offset:17216
	ds_read_b128 v[148:151], v148 offset:25664
	s_or_b32 s0, s0, 1
	s_waitcnt lgkmcnt(0)
	v_mfma_f32_16x16x32_f16 v[12:15], v[128:131], v[132:135], v[12:15]
	v_mfma_f32_16x16x32_f16 v[16:19], v[128:131], v[136:139], v[16:19]
	v_mfma_f32_16x16x32_f16 v[32:35], v[128:131], v[144:147], v[32:35]
	v_mfma_f32_16x16x32_f16 v[48:51], v[128:131], v[148:151], v[48:51]
	v_mfma_f32_16x16x32_f16 v[8:11], v[140:143], v[132:135], v[8:11]
	v_mfma_f32_16x16x32_f16 v[20:23], v[140:143], v[136:139], v[20:23]
	v_mfma_f32_16x16x32_f16 v[36:39], v[140:143], v[144:147], v[36:39]
	v_mfma_f32_16x16x32_f16 v[52:55], v[140:143], v[148:151], v[52:55]
	ds_read_b128 v[128:131], v154 offset:2048
	ds_read_b128 v[140:143], v154 offset:3072
	s_waitcnt lgkmcnt(0)
	v_mfma_f32_16x16x32_f16 v[4:7], v[128:131], v[132:135], v[4:7]
	v_mfma_f32_16x16x32_f16 v[24:27], v[128:131], v[136:139], v[24:27]
	v_mfma_f32_16x16x32_f16 v[40:43], v[128:131], v[144:147], v[40:43]
	v_mfma_f32_16x16x32_f16 v[116:119], v[128:131], v[148:151], v[116:119]
	v_xor_b32_e32 v128, v152, v169
	v_lshlrev_b32_e32 v128, 4, v128
	v_and_b32_e32 v224, 48, v128
	v_mfma_f32_16x16x32_f16 v[0:3], v[140:143], v[132:135], v[0:3]
	v_and_or_b32 v132, v153, 15, v246
	v_lshl_add_u32 v130, s18, 5, v132
	v_ashrrev_i32_e32 v131, 31, v130
	v_lshl_add_u64 v[128:129], s[16:17], 0, v[224:225]
	v_lshlrev_b64 v[130:131], 9, v[130:131]
	v_lshl_add_u64 v[130:131], v[128:129], 0, v[130:131]
	v_lshl_add_u64 v[130:131], v[130:131], 0, 64
	global_load_lds_dwordx4 v[130:131], off
	v_lshl_add_u32 v130, s0, 4, v132
	v_ashrrev_i32_e32 v131, 31, v130
	v_lshlrev_b64 v[130:131], 9, v[130:131]
	v_lshl_add_u64 v[128:129], v[128:129], 0, v[130:131]
	s_lshl_b32 s0, s0, 10
	v_lshl_add_u64 v[128:129], v[128:129], 0, 64
	s_add_i32 m0, s35, s0
	v_mfma_f32_16x16x32_f16 v[120:123], v[140:143], v[148:151], v[120:123]
	global_load_lds_dwordx4 v[128:129], off
	s_waitcnt vmcnt(6) lgkmcnt(0)
	s_barrier
	s_lshl_b32 s0, s18, 4
	v_and_b32_e32 v128, 15, v169
	s_and_b32 s0, s0, 0xfffffc0
	v_or_b32_e32 v132, s0, v128
	v_lshrrev_b32_e32 v160, 4, v169
	s_lshl_b32 s0, s18, 6
	v_lshrrev_b32_e32 v161, 2, v169
	s_and_b32 s0, s0, 0xc0
	v_xor_b32_e32 v129, v160, v161
	v_or_b32_e32 v128, s0, v128
	v_lshlrev_b32_e32 v129, 4, v129
	v_and_b32_e32 v129, 48, v129
	v_lshlrev_b32_e32 v128, 6, v128
	v_add3_u32 v152, s8, v129, v128
	ds_read_b128 v[128:131], v152
	v_and_b32_e32 v133, 48, v169
	v_mul_lo_u32 v132, v132, s7
	v_add3_u32 v148, 0, v133, v132
	v_mfma_f32_16x16x32_f16 v[28:31], v[140:143], v[136:139], v[28:31]
	s_lshl_b32 s0, s18, 1
	s_lshl_b32 s2, s18, 11
	s_add_i32 m0, s30, s2
	v_mfma_f32_16x16x32_f16 v[44:47], v[140:143], v[144:147], v[44:47]
	ds_read_b128 v[132:135], v148 offset:384
	ds_read_b128 v[136:139], v148 offset:8832
	ds_read_b128 v[140:143], v152 offset:1024
	ds_read_b128 v[144:147], v148 offset:17280
	ds_read_b128 v[148:151], v148 offset:25728
	s_or_b32 s0, s0, 1
	s_waitcnt lgkmcnt(0)
	v_mfma_f32_16x16x32_f16 v[12:15], v[128:131], v[132:135], v[12:15]
	v_mfma_f32_16x16x32_f16 v[16:19], v[128:131], v[136:139], v[16:19]
	v_mfma_f32_16x16x32_f16 v[32:35], v[128:131], v[144:147], v[32:35]
	v_mfma_f32_16x16x32_f16 v[128:131], v[128:131], v[148:151], v[48:51]
	v_mfma_f32_16x16x32_f16 v[8:11], v[140:143], v[132:135], v[8:11]
	v_mfma_f32_16x16x32_f16 v[20:23], v[140:143], v[136:139], v[20:23]
	v_mfma_f32_16x16x32_f16 v[36:39], v[140:143], v[144:147], v[36:39]
	v_mfma_f32_16x16x32_f16 v[140:143], v[140:143], v[148:151], v[52:55]
	ds_read_b128 v[48:51], v152 offset:2048
	s_nop 1
	ds_read_b128 v[52:55], v152 offset:3072
	s_waitcnt lgkmcnt(0)
	v_mfma_f32_16x16x32_f16 v[4:7], v[48:51], v[132:135], v[4:7]
	v_mfma_f32_16x16x32_f16 v[152:155], v[48:51], v[144:147], v[40:43]
	v_mfma_f32_16x16x32_f16 v[0:3], v[52:55], v[132:135], v[0:3]
	s_nop 1
	v_and_or_b32 v40, v161, 15, v246
	v_mfma_f32_16x16x32_f16 v[132:135], v[52:55], v[136:139], v[28:31]
	s_nop 2
	v_xor_b32_e32 v28, v160, v169
	v_lshlrev_b32_e32 v28, 4, v28
	v_lshl_add_u32 v30, s18, 5, v40
	v_and_b32_e32 v224, 48, v28
	v_ashrrev_i32_e32 v31, 31, v30
	v_lshl_add_u64 v[28:29], s[16:17], 0, v[224:225]
	v_lshlrev_b64 v[30:31], 9, v[30:31]
	v_lshl_add_u64 v[30:31], v[28:29], 0, v[30:31]
	v_lshl_add_u64 v[30:31], v[30:31], 0, s[24:25]
	global_load_lds_dwordx4 v[30:31], off
	v_lshl_add_u32 v30, s0, 4, v40
	v_ashrrev_i32_e32 v31, 31, v30
	v_lshlrev_b64 v[30:31], 9, v[30:31]
	v_lshl_add_u64 v[28:29], v[28:29], 0, v[30:31]
	s_lshl_b32 s0, s0, 10
	v_lshl_add_u64 v[28:29], v[28:29], 0, s[24:25]
	s_add_i32 m0, s30, s0
	v_mfma_f32_16x16x32_f16 v[24:27], v[48:51], v[136:139], v[24:27]
	global_load_lds_dwordx4 v[28:29], off
	s_waitcnt vmcnt(6) lgkmcnt(0)
	s_barrier
	s_lshl_b32 s0, s18, 4
	v_and_b32_e32 v28, 15, v169
	s_andn2_b32 s0, s0, 63
	v_or_b32_e32 v171, s0, v28
	v_lshrrev_b32_e32 v168, 4, v169
	s_lshl_b32 s0, s18, 6
	v_lshrrev_b32_e32 v170, 2, v169
	s_and_b32 s0, s0, 0xc0
	v_xor_b32_e32 v29, v168, v170
	v_or_b32_e32 v28, s0, v28
	v_lshlrev_b32_e32 v29, 4, v29
	v_and_b32_e32 v29, 48, v29
	v_lshlrev_b32_e32 v28, 6, v28
	v_add3_u32 v180, s31, v29, v28
	ds_read_b128 v[28:31], v180
	v_and_b32_e32 v40, 48, v169
	v_mul_lo_u32 v41, v171, s7
	v_add3_u32 v40, 0, v40, v41
	v_mfma_f32_16x16x32_f16 v[156:159], v[48:51], v[148:151], v[116:119]
	s_lshl_b32 s0, s18, 1
	s_lshl_b32 s2, s18, 11
	s_add_i32 m0, s8, s2
	v_mfma_f32_16x16x32_f16 v[136:139], v[52:55], v[144:147], v[44:47]
	s_or_b32 s0, s0, 1
	v_mfma_f32_16x16x32_f16 v[144:147], v[52:55], v[148:151], v[120:123]
	ds_read_b128 v[148:151], v40 offset:448
	ds_read_b128 v[160:163], v40 offset:8896
	ds_read_b128 v[164:167], v180 offset:1024
	ds_read_b128 v[172:175], v40 offset:17344
	ds_read_b128 v[176:179], v40 offset:25792
	s_waitcnt lgkmcnt(0)
	v_mfma_f32_16x16x32_f16 v[44:47], v[28:31], v[176:179], v[128:131]
	v_mfma_f32_16x16x32_f16 v[52:55], v[164:167], v[148:151], v[8:11]
	s_nop 2
	ds_read_b128 v[8:11], v180 offset:2048
	ds_read_b128 v[128:131], v180 offset:3072
	v_mfma_f32_16x16x32_f16 v[120:123], v[28:31], v[148:151], v[12:15]
	v_mfma_f32_16x16x32_f16 v[116:119], v[28:31], v[160:163], v[16:19]
	v_mfma_f32_16x16x32_f16 v[48:51], v[28:31], v[172:175], v[32:35]
	v_mfma_f32_16x16x32_f16 v[40:43], v[164:167], v[160:163], v[20:23]
	s_waitcnt lgkmcnt(0)
	v_mfma_f32_16x16x32_f16 v[32:35], v[8:11], v[148:151], v[4:7]
	v_mfma_f32_16x16x32_f16 v[20:23], v[8:11], v[160:163], v[24:27]
	v_mfma_f32_16x16x32_f16 v[16:19], v[8:11], v[172:175], v[152:155]
	v_mfma_f32_16x16x32_f16 v[12:15], v[8:11], v[176:179], v[156:159]
	v_mfma_f32_16x16x32_f16 v[24:27], v[128:131], v[148:151], v[0:3]
	v_mfma_f32_16x16x32_f16 v[8:11], v[128:131], v[160:163], v[132:135]
	v_mfma_f32_16x16x32_f16 v[4:7], v[128:131], v[172:175], v[136:139]
	s_nop 1
	v_and_or_b32 v132, v170, 15, v246
	v_mfma_f32_16x16x32_f16 v[0:3], v[128:131], v[176:179], v[144:147]
	v_xor_b32_e32 v128, v168, v169
	v_lshlrev_b32_e32 v128, 4, v128
	v_lshl_add_u32 v130, s18, 5, v132
	v_and_b32_e32 v224, 48, v128
	v_ashrrev_i32_e32 v131, 31, v130
	v_lshl_add_u64 v[128:129], s[16:17], 0, v[224:225]
	v_lshlrev_b64 v[130:131], 9, v[130:131]
	v_lshl_add_u64 v[130:131], v[128:129], 0, v[130:131]
	v_lshl_add_u64 v[130:131], v[130:131], 0, s[46:47]
	global_load_lds_dwordx4 v[130:131], off
	v_lshl_add_u32 v130, s0, 4, v132
	v_ashrrev_i32_e32 v131, 31, v130
	v_lshlrev_b64 v[130:131], 9, v[130:131]
	v_lshl_add_u64 v[128:129], v[128:129], 0, v[130:131]
	s_lshl_b32 s0, s0, 10
	v_lshl_add_u64 v[128:129], v[128:129], 0, s[46:47]
	s_add_i32 m0, s8, s0
	v_mfma_f32_16x16x32_f16 v[28:31], v[164:167], v[176:179], v[140:143]
	global_load_lds_dwordx4 v[128:129], off
	s_waitcnt vmcnt(6) lgkmcnt(0)
	s_barrier
	s_lshl_b32 s0, s18, 4
	v_and_b32_e32 v128, 15, v169
	s_and_b32 s0, s0, 0xfffffc0
	v_or_b32_e32 v132, s0, v128
	v_lshrrev_b32_e32 v152, 4, v169
	s_lshl_b32 s0, s18, 6
	v_lshrrev_b32_e32 v153, 2, v169
	s_and_b32 s0, s0, 0xc0
	v_xor_b32_e32 v129, v152, v153
	v_or_b32_e32 v128, s0, v128
	v_lshlrev_b32_e32 v129, 4, v129
	v_and_b32_e32 v129, 48, v129
	v_lshlrev_b32_e32 v128, 6, v128
	v_add3_u32 v154, s33, v129, v128
	ds_read_b128 v[128:131], v154
	v_and_b32_e32 v133, 48, v169
	v_mul_lo_u32 v132, v132, s7
	v_add3_u32 v148, 0, v133, v132
	ds_read_b128 v[132:135], v148
	ds_read_b128 v[136:139], v148 offset:8448
	ds_read_b128 v[140:143], v154 offset:1024
	ds_read_b128 v[144:147], v148 offset:16896
	ds_read_b128 v[148:151], v148 offset:25344
	s_waitcnt lgkmcnt(0)
	v_mfma_f32_16x16x32_f16 v[68:71], v[128:131], v[132:135], v[68:71]
	s_lshl_b32 s0, s18, 1
	s_lshl_b32 s2, s18, 11
	s_add_i32 m0, s31, s2
	v_mfma_f32_16x16x32_f16 v[84:87], v[128:131], v[136:139], v[84:87]
	s_or_b32 s0, s0, 1
	v_mfma_f32_16x16x32_f16 v[100:103], v[128:131], v[144:147], v[100:103]
	v_mfma_f32_16x16x32_f16 v[124:127], v[128:131], v[148:151], v[124:127]
	v_mfma_f32_16x16x32_f16 v[64:67], v[140:143], v[132:135], v[64:67]
	v_mfma_f32_16x16x32_f16 v[80:83], v[140:143], v[136:139], v[80:83]
	v_mfma_f32_16x16x32_f16 v[96:99], v[140:143], v[144:147], v[96:99]
	v_mfma_f32_16x16x32_f16 v[112:115], v[140:143], v[148:151], v[112:115]
	ds_read_b128 v[128:131], v154 offset:2048
	ds_read_b128 v[140:143], v154 offset:3072
	s_waitcnt lgkmcnt(0)
	v_mfma_f32_16x16x32_f16 v[60:63], v[128:131], v[132:135], v[60:63]
	v_mfma_f32_16x16x32_f16 v[76:79], v[128:131], v[136:139], v[76:79]
	v_mfma_f32_16x16x32_f16 v[92:95], v[128:131], v[144:147], v[92:95]
	v_mfma_f32_16x16x32_f16 v[108:111], v[128:131], v[148:151], v[108:111]
	v_xor_b32_e32 v128, v152, v169
	v_lshlrev_b32_e32 v128, 4, v128
	v_and_b32_e32 v224, 48, v128
	v_mfma_f32_16x16x32_f16 v[56:59], v[140:143], v[132:135], v[56:59]
	v_and_or_b32 v132, v153, 15, v246
	v_lshl_add_u32 v130, s18, 5, v132
	v_ashrrev_i32_e32 v131, 31, v130
	v_lshl_add_u64 v[128:129], s[16:17], 0, v[224:225]
	v_lshlrev_b64 v[130:131], 9, v[130:131]
	v_lshl_add_u64 v[130:131], v[128:129], 0, v[130:131]
	v_lshl_add_u64 v[130:131], v[130:131], 0, s[38:39]
	global_load_lds_dwordx4 v[130:131], off
	v_lshl_add_u32 v130, s0, 4, v132
	v_ashrrev_i32_e32 v131, 31, v130
	v_lshlrev_b64 v[130:131], 9, v[130:131]
	v_lshl_add_u64 v[128:129], v[128:129], 0, v[130:131]
	s_lshl_b32 s0, s0, 10
	v_lshl_add_u64 v[128:129], v[128:129], 0, s[38:39]
	s_add_i32 m0, s31, s0
	v_mfma_f32_16x16x32_f16 v[104:107], v[140:143], v[148:151], v[104:107]
	global_load_lds_dwordx4 v[128:129], off
	s_waitcnt vmcnt(6) lgkmcnt(0)
	s_barrier
	s_lshl_b32 s0, s18, 4
	v_and_b32_e32 v128, 15, v169
	s_and_b32 s0, s0, 0xfffffc0
	v_or_b32_e32 v132, s0, v128
	v_lshrrev_b32_e32 v152, 4, v169
	s_lshl_b32 s0, s18, 6
	v_lshrrev_b32_e32 v153, 2, v169
	s_and_b32 s0, s0, 0xc0
	v_xor_b32_e32 v129, v152, v153
	v_or_b32_e32 v128, s0, v128
	v_lshlrev_b32_e32 v129, 4, v129
	v_and_b32_e32 v129, 48, v129
	v_lshlrev_b32_e32 v128, 6, v128
	v_add3_u32 v154, s35, v129, v128
	ds_read_b128 v[128:131], v154
	v_and_b32_e32 v133, 48, v169
	v_mul_lo_u32 v132, v132, s7
	v_add3_u32 v148, 0, v133, v132
	v_mfma_f32_16x16x32_f16 v[72:75], v[140:143], v[136:139], v[72:75]
	s_lshl_b32 s0, s18, 1
	s_lshl_b32 s2, s18, 11
	s_add_i32 m0, s33, s2
	v_mfma_f32_16x16x32_f16 v[88:91], v[140:143], v[144:147], v[88:91]
	ds_read_b128 v[132:135], v148 offset:64
	ds_read_b128 v[136:139], v148 offset:8512
	ds_read_b128 v[140:143], v154 offset:1024
	ds_read_b128 v[144:147], v148 offset:16960
	ds_read_b128 v[148:151], v148 offset:25408
	s_or_b32 s0, s0, 1
	s_waitcnt lgkmcnt(0)
	v_mfma_f32_16x16x32_f16 v[68:71], v[128:131], v[132:135], v[68:71]
	v_mfma_f32_16x16x32_f16 v[84:87], v[128:131], v[136:139], v[84:87]
	v_mfma_f32_16x16x32_f16 v[100:103], v[128:131], v[144:147], v[100:103]
	v_mfma_f32_16x16x32_f16 v[124:127], v[128:131], v[148:151], v[124:127]
	v_mfma_f32_16x16x32_f16 v[64:67], v[140:143], v[132:135], v[64:67]
	v_mfma_f32_16x16x32_f16 v[80:83], v[140:143], v[136:139], v[80:83]
	v_mfma_f32_16x16x32_f16 v[96:99], v[140:143], v[144:147], v[96:99]
	v_mfma_f32_16x16x32_f16 v[112:115], v[140:143], v[148:151], v[112:115]
	ds_read_b128 v[128:131], v154 offset:2048
	ds_read_b128 v[140:143], v154 offset:3072
	s_waitcnt lgkmcnt(0)
	v_mfma_f32_16x16x32_f16 v[60:63], v[128:131], v[132:135], v[60:63]
	v_mfma_f32_16x16x32_f16 v[76:79], v[128:131], v[136:139], v[76:79]
	v_mfma_f32_16x16x32_f16 v[92:95], v[128:131], v[144:147], v[92:95]
	v_mfma_f32_16x16x32_f16 v[108:111], v[128:131], v[148:151], v[108:111]
	v_xor_b32_e32 v128, v152, v169
	v_lshlrev_b32_e32 v128, 4, v128
	v_and_b32_e32 v224, 48, v128
	v_mfma_f32_16x16x32_f16 v[56:59], v[140:143], v[132:135], v[56:59]
	v_and_or_b32 v132, v153, 15, v246
	v_lshl_add_u32 v130, s18, 5, v132
	v_ashrrev_i32_e32 v131, 31, v130
	v_lshl_add_u64 v[128:129], s[16:17], 0, v[224:225]
	v_lshlrev_b64 v[130:131], 9, v[130:131]
	v_lshl_add_u64 v[130:131], v[128:129], 0, v[130:131]
	v_lshl_add_u64 v[130:131], v[130:131], 0, s[48:49]
	global_load_lds_dwordx4 v[130:131], off
	v_lshl_add_u32 v130, s0, 4, v132
	v_ashrrev_i32_e32 v131, 31, v130
	v_lshlrev_b64 v[130:131], 9, v[130:131]
	v_lshl_add_u64 v[128:129], v[128:129], 0, v[130:131]
	s_lshl_b32 s0, s0, 10
	v_lshl_add_u64 v[128:129], v[128:129], 0, s[48:49]
	s_add_i32 m0, s33, s0
	v_mfma_f32_16x16x32_f16 v[104:107], v[140:143], v[148:151], v[104:107]
	global_load_lds_dwordx4 v[128:129], off
	s_waitcnt vmcnt(6) lgkmcnt(0)
	s_barrier
	s_lshl_b32 s0, s18, 4
	v_and_b32_e32 v128, 15, v169
	s_and_b32 s0, s0, 0xfffffc0
	v_or_b32_e32 v132, s0, v128
	v_lshrrev_b32_e32 v152, 4, v169
	s_lshl_b32 s0, s18, 6
	v_lshrrev_b32_e32 v153, 2, v169
	s_and_b32 s0, s0, 0xc0
	v_xor_b32_e32 v129, v152, v153
	v_or_b32_e32 v128, s0, v128
	v_lshlrev_b32_e32 v129, 4, v129
	v_and_b32_e32 v129, 48, v129
	v_lshlrev_b32_e32 v128, 6, v128
	v_add3_u32 v154, s30, v129, v128
	ds_read_b128 v[128:131], v154
	v_and_b32_e32 v133, 48, v169
	v_mul_lo_u32 v132, v132, s7
	v_add3_u32 v148, 0, v133, v132
	v_mfma_f32_16x16x32_f16 v[72:75], v[140:143], v[136:139], v[72:75]
	s_lshl_b32 s0, s18, 1
	s_lshl_b32 s2, s18, 11
	s_add_i32 m0, s35, s2
	v_mfma_f32_16x16x32_f16 v[88:91], v[140:143], v[144:147], v[88:91]
	ds_read_b128 v[132:135], v148 offset:128
	ds_read_b128 v[136:139], v148 offset:8576
	ds_read_b128 v[140:143], v154 offset:1024
	ds_read_b128 v[144:147], v148 offset:17024
	ds_read_b128 v[148:151], v148 offset:25472
	s_or_b32 s0, s0, 1
	s_waitcnt lgkmcnt(0)
	v_mfma_f32_16x16x32_f16 v[68:71], v[128:131], v[132:135], v[68:71]
	v_mfma_f32_16x16x32_f16 v[84:87], v[128:131], v[136:139], v[84:87]
	v_mfma_f32_16x16x32_f16 v[100:103], v[128:131], v[144:147], v[100:103]
	v_mfma_f32_16x16x32_f16 v[124:127], v[128:131], v[148:151], v[124:127]
	v_mfma_f32_16x16x32_f16 v[64:67], v[140:143], v[132:135], v[64:67]
	v_mfma_f32_16x16x32_f16 v[80:83], v[140:143], v[136:139], v[80:83]
	v_mfma_f32_16x16x32_f16 v[96:99], v[140:143], v[144:147], v[96:99]
	v_mfma_f32_16x16x32_f16 v[112:115], v[140:143], v[148:151], v[112:115]
	ds_read_b128 v[128:131], v154 offset:2048
	ds_read_b128 v[140:143], v154 offset:3072
	s_waitcnt lgkmcnt(0)
	v_mfma_f32_16x16x32_f16 v[60:63], v[128:131], v[132:135], v[60:63]
	v_mfma_f32_16x16x32_f16 v[76:79], v[128:131], v[136:139], v[76:79]
	v_mfma_f32_16x16x32_f16 v[92:95], v[128:131], v[144:147], v[92:95]
	v_mfma_f32_16x16x32_f16 v[108:111], v[128:131], v[148:151], v[108:111]
	v_xor_b32_e32 v128, v152, v169
	v_lshlrev_b32_e32 v128, 4, v128
	v_and_b32_e32 v224, 48, v128
	v_mfma_f32_16x16x32_f16 v[56:59], v[140:143], v[132:135], v[56:59]
	v_and_or_b32 v132, v153, 15, v246
	v_lshl_add_u32 v130, s18, 5, v132
	v_ashrrev_i32_e32 v131, 31, v130
	v_lshl_add_u64 v[128:129], s[16:17], 0, v[224:225]
	v_lshlrev_b64 v[130:131], 9, v[130:131]
	v_lshl_add_u64 v[130:131], v[128:129], 0, v[130:131]
	v_lshl_add_u64 v[130:131], v[130:131], 0, s[44:45]
	global_load_lds_dwordx4 v[130:131], off
	v_lshl_add_u32 v130, s0, 4, v132
	v_ashrrev_i32_e32 v131, 31, v130
	v_lshlrev_b64 v[130:131], 9, v[130:131]
	v_lshl_add_u64 v[128:129], v[128:129], 0, v[130:131]
	s_lshl_b32 s0, s0, 10
	v_lshl_add_u64 v[128:129], v[128:129], 0, s[44:45]
	s_add_i32 m0, s35, s0
	v_mfma_f32_16x16x32_f16 v[104:107], v[140:143], v[148:151], v[104:107]
	global_load_lds_dwordx4 v[128:129], off
	s_waitcnt vmcnt(6) lgkmcnt(0)
	s_barrier
	s_lshl_b32 s0, s18, 4
	v_and_b32_e32 v128, 15, v169
	s_and_b32 s0, s0, 0xfffffc0
	v_or_b32_e32 v132, s0, v128
	v_lshrrev_b32_e32 v152, 4, v169
	s_lshl_b32 s0, s18, 6
	v_lshrrev_b32_e32 v153, 2, v169
	s_and_b32 s0, s0, 0xc0
	v_xor_b32_e32 v129, v152, v153
	v_or_b32_e32 v128, s0, v128
	v_lshlrev_b32_e32 v129, 4, v129
	v_and_b32_e32 v129, 48, v129
	v_lshlrev_b32_e32 v128, 6, v128
	v_add3_u32 v154, s8, v129, v128
	ds_read_b128 v[128:131], v154
	v_and_b32_e32 v133, 48, v169
	v_mul_lo_u32 v132, v132, s7
	v_add3_u32 v148, 0, v133, v132
	v_mfma_f32_16x16x32_f16 v[72:75], v[140:143], v[136:139], v[72:75]
	s_lshl_b32 s0, s18, 1
	s_lshl_b32 s2, s18, 11
	s_add_i32 m0, s30, s2
	v_mfma_f32_16x16x32_f16 v[88:91], v[140:143], v[144:147], v[88:91]
	ds_read_b128 v[132:135], v148 offset:192
	ds_read_b128 v[136:139], v148 offset:8640
	ds_read_b128 v[140:143], v154 offset:1024
	ds_read_b128 v[144:147], v148 offset:17088
	ds_read_b128 v[148:151], v148 offset:25536
	s_or_b32 s0, s0, 1
	s_waitcnt lgkmcnt(0)
	v_mfma_f32_16x16x32_f16 v[68:71], v[128:131], v[132:135], v[68:71]
	v_mfma_f32_16x16x32_f16 v[84:87], v[128:131], v[136:139], v[84:87]
	v_mfma_f32_16x16x32_f16 v[100:103], v[128:131], v[144:147], v[100:103]
	v_mfma_f32_16x16x32_f16 v[124:127], v[128:131], v[148:151], v[124:127]
	v_mfma_f32_16x16x32_f16 v[64:67], v[140:143], v[132:135], v[64:67]
	v_mfma_f32_16x16x32_f16 v[80:83], v[140:143], v[136:139], v[80:83]
	v_mfma_f32_16x16x32_f16 v[96:99], v[140:143], v[144:147], v[96:99]
	v_mfma_f32_16x16x32_f16 v[112:115], v[140:143], v[148:151], v[112:115]
	ds_read_b128 v[128:131], v154 offset:2048
	ds_read_b128 v[140:143], v154 offset:3072
	s_waitcnt lgkmcnt(0)
	v_mfma_f32_16x16x32_f16 v[60:63], v[128:131], v[132:135], v[60:63]
	v_mfma_f32_16x16x32_f16 v[76:79], v[128:131], v[136:139], v[76:79]
	v_mfma_f32_16x16x32_f16 v[92:95], v[128:131], v[144:147], v[92:95]
	v_mfma_f32_16x16x32_f16 v[108:111], v[128:131], v[148:151], v[108:111]
	v_xor_b32_e32 v128, v152, v169
	v_lshlrev_b32_e32 v128, 4, v128
	v_and_b32_e32 v224, 48, v128
	v_mfma_f32_16x16x32_f16 v[56:59], v[140:143], v[132:135], v[56:59]
	v_and_or_b32 v132, v153, 15, v246
	v_lshl_add_u32 v130, s18, 5, v132
	v_ashrrev_i32_e32 v131, 31, v130
	v_lshl_add_u64 v[128:129], s[16:17], 0, v[224:225]
	v_lshlrev_b64 v[130:131], 9, v[130:131]
	v_lshl_add_u64 v[130:131], v[128:129], 0, v[130:131]
	v_lshl_add_u64 v[130:131], v[130:131], 0, s[50:51]
	global_load_lds_dwordx4 v[130:131], off
	v_lshl_add_u32 v130, s0, 4, v132
	v_ashrrev_i32_e32 v131, 31, v130
	v_lshlrev_b64 v[130:131], 9, v[130:131]
	v_lshl_add_u64 v[128:129], v[128:129], 0, v[130:131]
	s_lshl_b32 s0, s0, 10
	v_lshl_add_u64 v[128:129], v[128:129], 0, s[50:51]
	s_add_i32 m0, s30, s0
	v_mfma_f32_16x16x32_f16 v[104:107], v[140:143], v[148:151], v[104:107]
	global_load_lds_dwordx4 v[128:129], off
	s_waitcnt vmcnt(6) lgkmcnt(0)
	s_barrier
	s_lshl_b32 s0, s18, 4
	v_and_b32_e32 v128, 15, v169
	s_and_b32 s0, s0, 0xfffffc0
	v_or_b32_e32 v132, s0, v128
	v_lshrrev_b32_e32 v152, 4, v169
	s_lshl_b32 s0, s18, 6
	v_lshrrev_b32_e32 v153, 2, v169
	s_and_b32 s0, s0, 0xc0
	v_xor_b32_e32 v129, v152, v153
	v_or_b32_e32 v128, s0, v128
	v_lshlrev_b32_e32 v129, 4, v129
	v_and_b32_e32 v129, 48, v129
	v_lshlrev_b32_e32 v128, 6, v128
	v_add3_u32 v154, s31, v129, v128
	ds_read_b128 v[128:131], v154
	v_and_b32_e32 v133, 48, v169
	v_mul_lo_u32 v132, v132, s7
	v_add3_u32 v148, 0, v133, v132
	v_mfma_f32_16x16x32_f16 v[72:75], v[140:143], v[136:139], v[72:75]
	s_lshl_b32 s0, s18, 1
	s_lshl_b32 s2, s18, 11
	s_add_i32 m0, s30, s2
	v_mfma_f32_16x16x32_f16 v[88:91], v[140:143], v[144:147], v[88:91]
	ds_read_b128 v[132:135], v148 offset:256
	ds_read_b128 v[136:139], v148 offset:8704
	ds_read_b128 v[140:143], v154 offset:1024
	ds_read_b128 v[144:147], v148 offset:17152
	ds_read_b128 v[148:151], v148 offset:25600
	s_or_b32 s0, s0, 1
	s_waitcnt lgkmcnt(0)
	v_mfma_f32_16x16x32_f16 v[68:71], v[128:131], v[132:135], v[68:71]
	v_mfma_f32_16x16x32_f16 v[84:87], v[128:131], v[136:139], v[84:87]
	v_mfma_f32_16x16x32_f16 v[100:103], v[128:131], v[144:147], v[100:103]
	v_mfma_f32_16x16x32_f16 v[124:127], v[128:131], v[148:151], v[124:127]
	v_mfma_f32_16x16x32_f16 v[64:67], v[140:143], v[132:135], v[64:67]
	v_mfma_f32_16x16x32_f16 v[80:83], v[140:143], v[136:139], v[80:83]
	v_mfma_f32_16x16x32_f16 v[96:99], v[140:143], v[144:147], v[96:99]
	v_mfma_f32_16x16x32_f16 v[112:115], v[140:143], v[148:151], v[112:115]
	ds_read_b128 v[128:131], v154 offset:2048
	ds_read_b128 v[140:143], v154 offset:3072
	s_waitcnt lgkmcnt(0)
	v_mfma_f32_16x16x32_f16 v[60:63], v[128:131], v[132:135], v[60:63]
	v_mfma_f32_16x16x32_f16 v[76:79], v[128:131], v[136:139], v[76:79]
	v_mfma_f32_16x16x32_f16 v[92:95], v[128:131], v[144:147], v[92:95]
	v_mfma_f32_16x16x32_f16 v[108:111], v[128:131], v[148:151], v[108:111]
	v_xor_b32_e32 v128, v152, v169
	v_lshlrev_b32_e32 v128, 4, v128
	v_and_b32_e32 v224, 48, v128
	v_mfma_f32_16x16x32_f16 v[56:59], v[140:143], v[132:135], v[56:59]
	v_and_or_b32 v132, v153, 15, v246
	v_lshl_add_u32 v130, s18, 5, v132
	v_ashrrev_i32_e32 v131, 31, v130
	v_lshl_add_u64 v[128:129], s[16:17], 0, v[224:225]
	v_lshlrev_b64 v[130:131], 9, v[130:131]
	v_lshl_add_u64 v[130:131], v[128:129], 0, v[130:131]
	v_lshl_add_u64 v[130:131], v[130:131], 0, s[50:51]
	global_load_lds_dwordx4 v[130:131], off
	v_lshl_add_u32 v130, s0, 4, v132
	v_ashrrev_i32_e32 v131, 31, v130
	v_lshlrev_b64 v[130:131], 9, v[130:131]
	v_lshl_add_u64 v[128:129], v[128:129], 0, v[130:131]
	s_lshl_b32 s0, s0, 10
	v_lshl_add_u64 v[128:129], v[128:129], 0, s[50:51]
	s_add_i32 m0, s30, s0
	v_mfma_f32_16x16x32_f16 v[104:107], v[140:143], v[148:151], v[104:107]
	global_load_lds_dwordx4 v[128:129], off
	s_waitcnt vmcnt(6) lgkmcnt(0)
	s_barrier
	s_lshl_b32 s0, s18, 4
	v_and_b32_e32 v128, 15, v169
	s_and_b32 s0, s0, 0xfffffc0
	v_or_b32_e32 v132, s0, v128
	v_lshrrev_b32_e32 v152, 4, v169
	s_lshl_b32 s0, s18, 6
	v_lshrrev_b32_e32 v153, 2, v169
	s_and_b32 s0, s0, 0xc0
	v_xor_b32_e32 v129, v152, v153
	v_or_b32_e32 v128, s0, v128
	v_lshlrev_b32_e32 v129, 4, v129
	v_and_b32_e32 v129, 48, v129
	v_lshlrev_b32_e32 v128, 6, v128
	v_add3_u32 v154, s33, v129, v128
	ds_read_b128 v[128:131], v154
	v_and_b32_e32 v133, 48, v169
	v_mul_lo_u32 v132, v132, s7
	v_add3_u32 v148, 0, v133, v132
	v_mfma_f32_16x16x32_f16 v[72:75], v[140:143], v[136:139], v[72:75]
	s_lshl_b32 s0, s18, 1
	s_lshl_b32 s2, s18, 11
	s_add_i32 m0, s30, s2
	v_mfma_f32_16x16x32_f16 v[88:91], v[140:143], v[144:147], v[88:91]
	ds_read_b128 v[132:135], v148 offset:320
	ds_read_b128 v[136:139], v148 offset:8768
	ds_read_b128 v[140:143], v154 offset:1024
	ds_read_b128 v[144:147], v148 offset:17216
	ds_read_b128 v[148:151], v148 offset:25664
	s_or_b32 s0, s0, 1
	s_waitcnt lgkmcnt(0)
	v_mfma_f32_16x16x32_f16 v[68:71], v[128:131], v[132:135], v[68:71]
	v_mfma_f32_16x16x32_f16 v[84:87], v[128:131], v[136:139], v[84:87]
	v_mfma_f32_16x16x32_f16 v[100:103], v[128:131], v[144:147], v[100:103]
	v_mfma_f32_16x16x32_f16 v[124:127], v[128:131], v[148:151], v[124:127]
	v_mfma_f32_16x16x32_f16 v[64:67], v[140:143], v[132:135], v[64:67]
	v_mfma_f32_16x16x32_f16 v[80:83], v[140:143], v[136:139], v[80:83]
	v_mfma_f32_16x16x32_f16 v[96:99], v[140:143], v[144:147], v[96:99]
	v_mfma_f32_16x16x32_f16 v[112:115], v[140:143], v[148:151], v[112:115]
	ds_read_b128 v[128:131], v154 offset:2048
	ds_read_b128 v[140:143], v154 offset:3072
	s_waitcnt lgkmcnt(0)
	v_mfma_f32_16x16x32_f16 v[60:63], v[128:131], v[132:135], v[60:63]
	v_mfma_f32_16x16x32_f16 v[76:79], v[128:131], v[136:139], v[76:79]
	v_mfma_f32_16x16x32_f16 v[92:95], v[128:131], v[144:147], v[92:95]
	v_mfma_f32_16x16x32_f16 v[108:111], v[128:131], v[148:151], v[108:111]
	v_xor_b32_e32 v128, v152, v169
	v_lshlrev_b32_e32 v128, 4, v128
	v_and_b32_e32 v224, 48, v128
	v_mfma_f32_16x16x32_f16 v[56:59], v[140:143], v[132:135], v[56:59]
	v_and_or_b32 v132, v153, 15, v246
	v_lshl_add_u32 v130, s18, 5, v132
	v_ashrrev_i32_e32 v131, 31, v130
	v_lshl_add_u64 v[128:129], s[16:17], 0, v[224:225]
	v_lshlrev_b64 v[130:131], 9, v[130:131]
	v_lshl_add_u64 v[130:131], v[128:129], 0, v[130:131]
	v_lshl_add_u64 v[130:131], v[130:131], 0, s[50:51]
	global_load_lds_dwordx4 v[130:131], off
	v_lshl_add_u32 v130, s0, 4, v132
	v_ashrrev_i32_e32 v131, 31, v130
	v_lshlrev_b64 v[130:131], 9, v[130:131]
	v_lshl_add_u64 v[128:129], v[128:129], 0, v[130:131]
	s_lshl_b32 s0, s0, 10
	v_lshl_add_u64 v[128:129], v[128:129], 0, s[50:51]
	s_add_i32 m0, s30, s0
	v_mfma_f32_16x16x32_f16 v[104:107], v[140:143], v[148:151], v[104:107]
	global_load_lds_dwordx4 v[128:129], off
	s_waitcnt vmcnt(6) lgkmcnt(0)
	s_barrier
	s_lshl_b32 s0, s18, 4
	v_and_b32_e32 v128, 15, v169
	s_and_b32 s0, s0, 0xfffffc0
	v_or_b32_e32 v132, s0, v128
	v_lshrrev_b32_e32 v168, 4, v169
	s_lshl_b32 s0, s18, 6
	v_lshrrev_b32_e32 v170, 2, v169
	s_and_b32 s0, s0, 0xc0
	v_xor_b32_e32 v129, v168, v170
	v_or_b32_e32 v128, s0, v128
	v_lshlrev_b32_e32 v129, 4, v129
	v_and_b32_e32 v129, 48, v129
	v_lshlrev_b32_e32 v128, 6, v128
	v_add3_u32 v160, s35, v129, v128
	ds_read_b128 v[128:131], v160
	v_and_b32_e32 v133, 48, v169
	v_mul_lo_u32 v132, v132, s7
	v_add3_u32 v148, 0, v133, v132
	v_mfma_f32_16x16x32_f16 v[72:75], v[140:143], v[136:139], v[72:75]
	s_lshl_b32 s0, s18, 1
	s_lshl_b32 s2, s18, 11
	s_add_i32 m0, s30, s2
	v_mfma_f32_16x16x32_f16 v[88:91], v[140:143], v[144:147], v[88:91]
	ds_read_b128 v[132:135], v148 offset:384
	ds_read_b128 v[136:139], v148 offset:8832
	ds_read_b128 v[140:143], v160 offset:1024
	ds_read_b128 v[144:147], v148 offset:17280
	ds_read_b128 v[148:151], v148 offset:25728
	s_or_b32 s0, s0, 1
	s_waitcnt lgkmcnt(0)
	v_mfma_f32_16x16x32_f16 v[152:155], v[128:131], v[148:151], v[124:127]
	v_mfma_f32_16x16x32_f16 v[156:159], v[140:143], v[144:147], v[96:99]
	s_nop 2
	ds_read_b128 v[96:99], v160 offset:2048
	ds_read_b128 v[124:127], v160 offset:3072
	s_waitcnt lgkmcnt(0)
	v_mfma_f32_16x16x32_f16 v[160:163], v[96:99], v[136:139], v[76:79]
	s_nop 2
	v_and_or_b32 v76, v170, 15, v246
	v_mfma_f32_16x16x32_f16 v[178:181], v[124:127], v[136:139], v[72:75]
	s_nop 2
	v_xor_b32_e32 v72, v168, v169
	v_lshlrev_b32_e32 v72, 4, v72
	v_lshl_add_u32 v74, s18, 5, v76
	v_and_b32_e32 v224, 48, v72
	v_ashrrev_i32_e32 v75, 31, v74
	v_lshl_add_u64 v[72:73], s[16:17], 0, v[224:225]
	v_lshlrev_b64 v[74:75], 9, v[74:75]
	v_lshl_add_u64 v[74:75], v[72:73], 0, v[74:75]
	v_lshl_add_u64 v[74:75], v[74:75], 0, s[50:51]
	global_load_lds_dwordx4 v[74:75], off
	v_lshl_add_u32 v74, s0, 4, v76
	v_ashrrev_i32_e32 v75, 31, v74
	v_lshlrev_b64 v[74:75], 9, v[74:75]
	v_lshl_add_u64 v[72:73], v[72:73], 0, v[74:75]
	s_lshl_b32 s0, s0, 10
	v_lshl_add_u64 v[72:73], v[72:73], 0, s[50:51]
	s_add_i32 m0, s30, s0
	v_mfma_f32_16x16x32_f16 v[36:39], v[164:167], v[172:175], v[36:39]
	global_load_lds_dwordx4 v[72:73], off
	s_waitcnt vmcnt(6) lgkmcnt(0)
	s_barrier
	s_lshl_b32 s0, s18, 4
	v_and_b32_e32 v72, 15, v169
	s_andn2_b32 s0, s0, 63
	v_or_b32_e32 v173, s0, v72
	v_lshrrev_b32_e32 v168, 4, v169
	s_lshl_b32 s0, s18, 6
	v_lshrrev_b32_e32 v170, 2, v169
	s_and_b32 s0, s0, 0xc0
	v_xor_b32_e32 v73, v168, v170
	v_or_b32_e32 v72, s0, v72
	v_lshlrev_b32_e32 v73, 4, v73
	v_and_b32_e32 v73, 48, v73
	v_lshlrev_b32_e32 v72, 6, v72
	v_mfma_f32_16x16x32_f16 v[68:71], v[128:131], v[132:135], v[68:71]
	v_and_b32_e32 v76, 48, v169
	v_mul_lo_u32 v77, v173, s7
	s_lshl_b32 s0, s18, 1
	v_mfma_f32_16x16x32_f16 v[64:67], v[140:143], v[132:135], v[64:67]
	s_lshl_b32 s2, s18, 11
	s_add_i32 m0, s30, s2
	s_or_b32 s0, s0, 1
	v_mfma_f32_16x16x32_f16 v[60:63], v[96:99], v[132:135], v[60:63]
	v_mfma_f32_16x16x32_f16 v[56:59], v[124:127], v[132:135], v[56:59]
	v_add3_u32 v132, s30, v73, v72
	ds_read_b128 v[72:75], v132
	v_mfma_f32_16x16x32_f16 v[80:83], v[140:143], v[136:139], v[80:83]
	v_mfma_f32_16x16x32_f16 v[140:143], v[140:143], v[148:151], v[112:115]
	v_mfma_f32_16x16x32_f16 v[112:115], v[124:127], v[144:147], v[88:91]
	s_nop 2
	v_add3_u32 v88, 0, v76, v77
	v_mfma_f32_16x16x32_f16 v[84:87], v[128:131], v[136:139], v[84:87]
	v_mfma_f32_16x16x32_f16 v[100:103], v[128:131], v[144:147], v[100:103]
	v_mfma_f32_16x16x32_f16 v[164:167], v[96:99], v[144:147], v[92:95]
	v_mfma_f32_16x16x32_f16 v[174:177], v[96:99], v[148:151], v[108:111]
	v_mfma_f32_16x16x32_f16 v[124:127], v[124:127], v[148:151], v[104:107]
	ds_read_b128 v[144:147], v88 offset:448
	ds_read_b128 v[148:151], v88 offset:8896
	ds_read_b128 v[76:79], v132 offset:1024
	ds_read_b128 v[136:139], v88 offset:17344
	ds_read_b128 v[128:131], v88 offset:25792
	s_waitcnt lgkmcnt(0)
	v_mfma_f32_16x16x32_f16 v[108:111], v[72:75], v[144:147], v[68:71]
	v_mfma_f32_16x16x32_f16 v[104:107], v[72:75], v[148:151], v[84:87]
	v_mfma_f32_16x16x32_f16 v[96:99], v[72:75], v[136:139], v[100:103]
	v_mfma_f32_16x16x32_f16 v[92:95], v[72:75], v[128:131], v[152:155]
	ds_read_b128 v[72:75], v132 offset:2048
	ds_read_b128 v[132:135], v132 offset:3072
	v_mfma_f32_16x16x32_f16 v[100:103], v[76:79], v[144:147], v[64:67]
	v_mfma_f32_16x16x32_f16 v[88:91], v[76:79], v[148:151], v[80:83]
	v_mfma_f32_16x16x32_f16 v[84:87], v[76:79], v[136:139], v[156:159]
	v_mfma_f32_16x16x32_f16 v[76:79], v[76:79], v[128:131], v[140:143]
	s_waitcnt lgkmcnt(0)
	v_mfma_f32_16x16x32_f16 v[80:83], v[72:75], v[144:147], v[60:63]
	s_nop 0
	v_xor_b32_e32 v140, v168, v169
	v_lshlrev_b32_e32 v140, 4, v140
	v_and_b32_e32 v224, 48, v140
	v_mfma_f32_16x16x32_f16 v[68:71], v[72:75], v[148:151], v[160:163]
	v_lshl_add_u64 v[140:141], s[16:17], 0, v[224:225]
	v_mfma_f32_16x16x32_f16 v[64:67], v[72:75], v[136:139], v[164:167]
	v_mfma_f32_16x16x32_f16 v[60:63], v[72:75], v[128:131], v[174:177]
	v_mfma_f32_16x16x32_f16 v[72:75], v[132:135], v[144:147], v[56:59]
	v_and_or_b32 v144, v170, 15, v246
	v_lshl_add_u32 v142, s18, 5, v144
	v_ashrrev_i32_e32 v143, 31, v142
	v_lshlrev_b64 v[142:143], 9, v[142:143]
	v_lshl_add_u64 v[142:143], v[140:141], 0, v[142:143]
	v_lshl_add_u64 v[142:143], v[142:143], 0, s[50:51]
	global_load_lds_dwordx4 v[142:143], off
	v_lshl_add_u32 v142, s0, 4, v144
	v_ashrrev_i32_e32 v143, 31, v142
	v_lshlrev_b64 v[142:143], 9, v[142:143]
	v_lshl_add_u64 v[140:141], v[140:141], 0, v[142:143]
	s_lshl_b32 s0, s0, 10
	v_lshl_add_u64 v[140:141], v[140:141], 0, s[50:51]
	s_add_i32 m0, s30, s0
	v_mfma_f32_16x16x32_f16 v[56:59], v[132:135], v[148:151], v[178:181]
	global_load_lds_dwordx4 v[140:141], off
	s_waitcnt vmcnt(0) lgkmcnt(0)
	s_barrier
	s_add_u32 s2, s19, s34
	v_add_u32_e32 v142, 0x200, v169
	v_lshlrev_b32_e32 v140, 4, v169
	v_ashrrev_i32_e32 v168, 5, v169
	v_ashrrev_i32_e32 v170, 5, v142
	v_and_b32_e32 v224, 0x1f0, v140
	v_add_u32_e32 v140, s42, v168
	v_add_u32_e32 v142, s42, v170
	v_add_u32_e32 v148, 0x400, v169
	v_add_u32_e32 v150, 0x600, v169
	s_addc_u32 s3, s20, 0
	v_ashrrev_i32_e32 v141, 31, v140
	v_ashrrev_i32_e32 v143, 31, v142
	v_ashrrev_i32_e32 v172, 5, v148
	v_ashrrev_i32_e32 v178, 5, v150
	v_lshl_add_u64 v[174:175], s[2:3], 0, v[224:225]
	v_lshlrev_b64 v[140:141], 12, v[140:141]
	v_lshlrev_b64 v[142:143], 12, v[142:143]
	v_add_u32_e32 v148, s42, v172
	v_add_u32_e32 v150, s42, v178
	v_add_u32_e32 v156, 0x800, v169
	v_add_u32_e32 v158, 0xa00, v169
	v_lshl_add_u64 v[140:141], v[174:175], 0, v[140:141]
	v_lshl_add_u64 v[144:145], v[174:175], 0, v[142:143]
	v_ashrrev_i32_e32 v149, 31, v148
	v_ashrrev_i32_e32 v151, 31, v150
	v_ashrrev_i32_e32 v179, 5, v156
	v_ashrrev_i32_e32 v180, 5, v158
	v_add_u32_e32 v164, 0xc00, v169
	v_add_u32_e32 v176, 0xe00, v169
	global_load_dwordx4 v[140:143], v[140:141], off
	s_nop 0
	global_load_dwordx4 v[144:147], v[144:145], off
	v_lshlrev_b64 v[148:149], 12, v[148:149]
	v_lshlrev_b64 v[150:151], 12, v[150:151]
	v_add_u32_e32 v156, s42, v179
	v_add_u32_e32 v158, s42, v180
	v_ashrrev_i32_e32 v181, 5, v164
	v_ashrrev_i32_e32 v182, 5, v176
	v_lshl_add_u64 v[148:149], v[174:175], 0, v[148:149]
	v_lshl_add_u64 v[152:153], v[174:175], 0, v[150:151]
	v_ashrrev_i32_e32 v157, 31, v156
	v_ashrrev_i32_e32 v159, 31, v158
	v_add_u32_e32 v164, s42, v181
	v_add_u32_e32 v176, s42, v182
	global_load_dwordx4 v[148:151], v[148:149], off
	s_nop 0
	global_load_dwordx4 v[152:155], v[152:153], off
	v_lshlrev_b64 v[156:157], 12, v[156:157]
	v_lshlrev_b64 v[158:159], 12, v[158:159]
	v_ashrrev_i32_e32 v165, 31, v164
	v_ashrrev_i32_e32 v177, 31, v176
	v_lshl_add_u64 v[156:157], v[174:175], 0, v[156:157]
	v_lshl_add_u64 v[160:161], v[174:175], 0, v[158:159]
	v_lshlrev_b64 v[164:165], 12, v[164:165]
	v_lshlrev_b64 v[176:177], 12, v[176:177]
	global_load_dwordx4 v[156:159], v[156:157], off
	s_nop 0
	global_load_dwordx4 v[160:163], v[160:161], off
	v_lshl_add_u64 v[164:165], v[174:175], 0, v[164:165]
	v_lshl_add_u64 v[174:175], v[174:175], 0, v[176:177]
	global_load_dwordx4 v[164:167], v[164:165], off
	v_mfma_f32_16x16x32_f16 v[112:115], v[132:135], v[136:139], v[112:115]
	global_load_dwordx4 v[174:177], v[174:175], off
	v_add_u32_e32 v136, s30, v224
	v_mad_u64_u32 v[138:139], s[2:3], v168, s7, v[136:137]
	s_ashr_i32 s43, s42, 31
	v_mfma_f32_16x16x32_f16 v[128:131], v[132:135], v[128:131], v[124:127]
	s_waitcnt vmcnt(0)
	ds_write_b128 v138, v[140:143]
	v_mad_u64_u32 v[138:139], s[2:3], v170, s7, v[136:137]
	ds_write_b128 v138, v[144:147]
	v_mad_u64_u32 v[138:139], s[2:3], v172, s7, v[136:137]
	ds_write_b128 v138, v[148:151]
	v_mad_u64_u32 v[138:139], s[2:3], v178, s7, v[136:137]
	ds_write_b128 v138, v[152:155]
	v_mad_u64_u32 v[138:139], s[2:3], v179, s7, v[136:137]
	ds_write_b128 v138, v[156:159]
	v_mad_u64_u32 v[138:139], s[2:3], v180, s7, v[136:137]
	ds_write_b128 v138, v[160:163]
	v_mad_u64_u32 v[138:139], s[2:3], v181, s7, v[136:137]
	v_mad_u64_u32 v[136:137], s[2:3], v182, s7, v[136:137]
	ds_write_b128 v138, v[164:167]
	ds_write_b128 v136, v[174:177]
	s_waitcnt lgkmcnt(0)
	s_barrier
	s_lshl_b32 s0, s18, 5
	v_and_b32_e32 v137, 15, v169
	s_and_b32 s0, s0, 0x60
	v_or_b32_e32 v136, s0, v137
	v_and_b32_e32 v166, 48, v169
	v_mul_u32_u24_e32 v136, 0x210, v136
	v_add3_u32 v136, s30, v166, v136
	v_mov_b32 v138, 0
	v_mov_b32 v139, 0
	v_mov_b32 v140, 0
	v_mov_b32 v141, 0
	v_mov_b32 v142, 0
	v_mov_b32 v143, 0
	v_mov_b32 v144, 0
	v_mov_b32 v145, 0
	v_mov_b32 v146, 0
	v_mov_b32 v147, 0
	v_mov_b32 v148, 0
	v_mov_b32 v149, 0
	v_mov_b32 v150, 0
	v_mov_b32 v151, 0
	v_mov_b32 v152, 0
	v_mov_b32 v153, 0
	v_mov_b32 v154, 0
	v_mov_b32 v155, 0
	v_mov_b32 v156, 0
	v_mov_b32 v157, 0
	v_mov_b32 v158, 0
	v_mov_b32 v159, 0
	v_mov_b32 v160, 0
	v_mov_b32 v161, 0
	v_mov_b32 v162, 0
	v_mov_b32 v163, 0
	v_mov_b32 v164, 0
	v_mov_b32 v165, 0
	v_mov_b32 v174, 0
	v_mov_b32 v175, 0
	v_mov_b32 v176, 0
	v_mov_b32 v177, 0
	s_lshl_b32 s0, s18, 4
	ds_read_b128 v[178:181], v136
	s_and_b32 s0, s0, 0xfffffc0
	v_or_b32_e32 v137, s0, v137
	v_mul_lo_u32 v137, v137, s7
	v_add3_u32 v137, 0, v166, v137
	ds_read_b128 v[182:185], v137
	ds_read_b128 v[186:189], v137 offset:64
	ds_read_b128 v[190:193], v136 offset:64
	ds_read_b128 v[194:197], v137 offset:8448
	ds_read_b128 v[198:201], v137 offset:8512
	ds_read_b128 v[202:205], v137 offset:16896
	ds_read_b128 v[206:209], v137 offset:16960
	ds_read_b128 v[210:213], v137 offset:25344
	ds_read_b128 v[214:217], v137 offset:25408
	s_waitcnt lgkmcnt(8)
	v_mfma_f32_16x16x32_f16 v[138:141], v[178:181], v[182:185], v[138:141]
	s_lshl_b64 s[2:3], s[42:43], 1
	s_movk_i32 s7, 0x110
	s_waitcnt lgkmcnt(5)
	v_mfma_f32_16x16x32_f16 v[146:149], v[178:181], v[194:197], v[146:149]
	s_waitcnt lgkmcnt(3)
	v_mfma_f32_16x16x32_f16 v[154:157], v[178:181], v[202:205], v[154:157]
	s_waitcnt lgkmcnt(1)
	v_mfma_f32_16x16x32_f16 v[162:165], v[178:181], v[210:213], v[162:165]
	ds_read_b128 v[178:181], v136 offset:8448
	ds_read_b128 v[218:221], v136 offset:8512
	s_waitcnt lgkmcnt(1)
	v_mfma_f32_16x16x32_f16 v[142:145], v[178:181], v[182:185], v[142:145]
	v_mfma_f32_16x16x32_f16 v[150:153], v[178:181], v[194:197], v[150:153]
	v_mfma_f32_16x16x32_f16 v[158:161], v[178:181], v[202:205], v[158:161]
	v_mfma_f32_16x16x32_f16 v[174:177], v[178:181], v[210:213], v[174:177]
	ds_read_b128 v[178:181], v136 offset:128
	v_mfma_f32_16x16x32_f16 v[138:141], v[190:193], v[186:189], v[138:141]
	v_mfma_f32_16x16x32_f16 v[146:149], v[190:193], v[198:201], v[146:149]
	v_mfma_f32_16x16x32_f16 v[154:157], v[190:193], v[206:209], v[154:157]
	v_mfma_f32_16x16x32_f16 v[162:165], v[190:193], v[214:217], v[162:165]
	s_waitcnt lgkmcnt(1)
	v_mfma_f32_16x16x32_f16 v[142:145], v[218:221], v[186:189], v[142:145]
	ds_read_b128 v[182:185], v137 offset:128
	ds_read_b128 v[186:189], v137 offset:192
	ds_read_b128 v[190:193], v136 offset:192
	v_mfma_f32_16x16x32_f16 v[150:153], v[218:221], v[198:201], v[150:153]
	ds_read_b128 v[194:197], v137 offset:8576
	ds_read_b128 v[198:201], v137 offset:8640
	v_mfma_f32_16x16x32_f16 v[158:161], v[218:221], v[206:209], v[158:161]
	ds_read_b128 v[202:205], v137 offset:17024
	ds_read_b128 v[206:209], v137 offset:17088
	v_mfma_f32_16x16x32_f16 v[174:177], v[218:221], v[214:217], v[174:177]
	ds_read_b128 v[210:213], v137 offset:25472
	ds_read_b128 v[214:217], v137 offset:25536
	s_waitcnt lgkmcnt(8)
	v_mfma_f32_16x16x32_f16 v[138:141], v[178:181], v[182:185], v[138:141]
	s_waitcnt lgkmcnt(5)
	v_mfma_f32_16x16x32_f16 v[146:149], v[178:181], v[194:197], v[146:149]
	s_waitcnt lgkmcnt(3)
	v_mfma_f32_16x16x32_f16 v[154:157], v[178:181], v[202:205], v[154:157]
	s_waitcnt lgkmcnt(1)
	v_mfma_f32_16x16x32_f16 v[162:165], v[178:181], v[210:213], v[162:165]
	ds_read_b128 v[178:181], v136 offset:8576
	ds_read_b128 v[218:221], v136 offset:8640
	s_waitcnt lgkmcnt(1)
	v_mfma_f32_16x16x32_f16 v[142:145], v[178:181], v[182:185], v[142:145]
	v_mfma_f32_16x16x32_f16 v[150:153], v[178:181], v[194:197], v[150:153]
	v_mfma_f32_16x16x32_f16 v[158:161], v[178:181], v[202:205], v[158:161]
	v_mfma_f32_16x16x32_f16 v[174:177], v[178:181], v[210:213], v[174:177]
	ds_read_b128 v[178:181], v136 offset:256
	v_mfma_f32_16x16x32_f16 v[138:141], v[190:193], v[186:189], v[138:141]
	v_mfma_f32_16x16x32_f16 v[146:149], v[190:193], v[198:201], v[146:149]
	v_mfma_f32_16x16x32_f16 v[154:157], v[190:193], v[206:209], v[154:157]
	v_mfma_f32_16x16x32_f16 v[162:165], v[190:193], v[214:217], v[162:165]
	s_waitcnt lgkmcnt(1)
	v_mfma_f32_16x16x32_f16 v[142:145], v[218:221], v[186:189], v[142:145]
	ds_read_b128 v[182:185], v137 offset:256
	ds_read_b128 v[186:189], v137 offset:320
	ds_read_b128 v[190:193], v136 offset:320
	v_mfma_f32_16x16x32_f16 v[150:153], v[218:221], v[198:201], v[150:153]
	ds_read_b128 v[194:197], v137 offset:8704
	ds_read_b128 v[198:201], v137 offset:8768
	v_mfma_f32_16x16x32_f16 v[158:161], v[218:221], v[206:209], v[158:161]
	ds_read_b128 v[202:205], v137 offset:17152
	ds_read_b128 v[206:209], v137 offset:17216
	v_mfma_f32_16x16x32_f16 v[174:177], v[218:221], v[214:217], v[174:177]
	ds_read_b128 v[210:213], v137 offset:25600
	ds_read_b128 v[214:217], v137 offset:25664
	s_waitcnt lgkmcnt(8)
	v_mfma_f32_16x16x32_f16 v[138:141], v[178:181], v[182:185], v[138:141]
	s_waitcnt lgkmcnt(5)
	v_mfma_f32_16x16x32_f16 v[146:149], v[178:181], v[194:197], v[146:149]
	s_waitcnt lgkmcnt(3)
	v_mfma_f32_16x16x32_f16 v[154:157], v[178:181], v[202:205], v[154:157]
	s_waitcnt lgkmcnt(1)
	v_mfma_f32_16x16x32_f16 v[162:165], v[178:181], v[210:213], v[162:165]
	ds_read_b128 v[178:181], v136 offset:8704
	ds_read_b128 v[218:221], v136 offset:8768
	s_waitcnt lgkmcnt(1)
	v_mfma_f32_16x16x32_f16 v[142:145], v[178:181], v[182:185], v[142:145]
	v_mfma_f32_16x16x32_f16 v[150:153], v[178:181], v[194:197], v[150:153]
	v_mfma_f32_16x16x32_f16 v[158:161], v[178:181], v[202:205], v[158:161]
	v_mfma_f32_16x16x32_f16 v[174:177], v[178:181], v[210:213], v[174:177]
	ds_read_b128 v[178:181], v136 offset:384
	v_mfma_f32_16x16x32_f16 v[138:141], v[190:193], v[186:189], v[138:141]
	v_mfma_f32_16x16x32_f16 v[146:149], v[190:193], v[198:201], v[146:149]
	v_mfma_f32_16x16x32_f16 v[154:157], v[190:193], v[206:209], v[154:157]
	v_mfma_f32_16x16x32_f16 v[162:165], v[190:193], v[214:217], v[162:165]
	s_waitcnt lgkmcnt(1)
	v_mfma_f32_16x16x32_f16 v[142:145], v[218:221], v[186:189], v[142:145]
	ds_read_b128 v[182:185], v137 offset:384
	ds_read_b128 v[186:189], v137 offset:448
	ds_read_b128 v[190:193], v136 offset:448
	v_mfma_f32_16x16x32_f16 v[150:153], v[218:221], v[198:201], v[150:153]
	ds_read_b128 v[194:197], v137 offset:8832
	ds_read_b128 v[198:201], v137 offset:8896
	v_mfma_f32_16x16x32_f16 v[158:161], v[218:221], v[206:209], v[158:161]
	ds_read_b128 v[202:205], v137 offset:17280
	ds_read_b128 v[206:209], v137 offset:17344
	v_mfma_f32_16x16x32_f16 v[174:177], v[218:221], v[214:217], v[174:177]
	s_waitcnt lgkmcnt(1)
	v_mfma_f32_16x16x32_f16 v[210:213], v[178:181], v[202:205], v[154:157]
	s_nop 2
	ds_read_b128 v[154:157], v137 offset:25728
	ds_read_b128 v[214:217], v137 offset:25792
	v_mfma_f32_16x16x32_f16 v[138:141], v[178:181], v[182:185], v[138:141]
	v_mfma_f32_16x16x32_f16 v[146:149], v[178:181], v[194:197], v[146:149]
	s_waitcnt lgkmcnt(1)
	v_mfma_f32_16x16x32_f16 v[178:181], v[178:181], v[154:157], v[162:165]
	s_nop 2
	ds_read_b128 v[162:165], v136 offset:8832
	ds_read_b128 v[218:221], v136 offset:8896
	v_add_u32_e32 v136, 1, v171
	v_cvt_f32_i32_e32 v136, v136
	s_waitcnt lgkmcnt(1)
	v_mfma_f32_16x16x32_f16 v[174:177], v[162:165], v[154:157], v[174:177]
	s_waitcnt lgkmcnt(0)
	v_mul_f32_e32 v136, s9, v136
	v_exp_f32_e32 v168, v136
	v_add_u32_e32 v136, 17, v171
	v_cvt_f32_i32_e32 v136, v136
	s_barrier
	v_pk_mul_f32 v[122:123], v[122:123], v[168:169] op_sel_hi:[1,0]
	v_pk_mul_f32 v[120:121], v[120:121], v[168:169] op_sel_hi:[1,0]
	v_mul_f32_e32 v136, s9, v136
	v_exp_f32_e32 v170, v136
	v_add_u32_e32 v136, 33, v171
	v_cvt_f32_i32_e32 v136, v136
	s_lshl_b32 s0, s18, 1
	v_mul_f32_e32 v136, s9, v136
	v_mfma_f32_16x16x32_f16 v[182:185], v[162:165], v[182:185], v[142:145]
	v_exp_f32_e32 v172, v136
	s_add_u32 s16, s21, s2
	s_addc_u32 s17, s22, s3
	v_mfma_f32_16x16x32_f16 v[194:197], v[162:165], v[194:197], v[150:153]
	s_lshl_b32 s2, s18, 5
	s_or_b32 s0, s0, 1
	s_lshl_b32 s3, s18, 11
	v_mfma_f32_16x16x32_f16 v[202:205], v[162:165], v[202:205], v[158:161]
	s_add_i32 m0, s8, s3
	v_pk_mul_f32 v[118:119], v[118:119], v[170:171] op_sel_hi:[1,0]
	v_pk_mul_f32 v[116:117], v[116:117], v[170:171] op_sel_hi:[1,0]
	v_mfma_f32_16x16x32_f16 v[164:167], v[190:193], v[186:189], v[138:141]
	v_mul_f32_e64 v50, v50, v172
	v_mul_f32_e64 v51, v51, v172
	v_pk_mul_f32 v[48:49], v[48:49], v[172:173] op_sel_hi:[1,0]
	v_pk_mul_f32 v[42:43], v[170:171], v[42:43] op_sel_hi:[0,1]
	v_mfma_f32_16x16x32_f16 v[140:143], v[190:193], v[214:217], v[178:181]
	v_mul_f32_e64 v40, v170, v40
	v_mul_f32_e64 v41, v170, v41
	v_pk_mul_f32 v[38:39], v[172:173], v[38:39] op_sel_hi:[0,1]
	v_pk_mul_f32 v[36:37], v[172:173], v[36:37] op_sel_hi:[0,1]
	v_mfma_f32_16x16x32_f16 v[136:139], v[218:221], v[214:217], v[174:177]
	v_lshrrev_b32_e32 v180, 2, v169
	v_and_or_b32 v178, v180, 15, s34
	v_pk_mul_f32 v[22:23], v[170:171], v[22:23] op_sel_hi:[0,1]
	v_lshrrev_b32_e32 v174, 4, v169
	v_xor_b32_e32 v174, v174, v169
	v_lshlrev_b32_e32 v174, 4, v174
	v_add_u32_e32 v176, s2, v178
	v_and_b32_e32 v224, 48, v174
	v_ashrrev_i32_e32 v177, 31, v176
	v_lshl_add_u32 v178, s0, 4, v178
	v_lshl_add_u64 v[174:175], s[16:17], 0, v[224:225]
	v_lshlrev_b64 v[176:177], 15, v[176:177]
	v_ashrrev_i32_e32 v179, 31, v178
	v_lshl_add_u64 v[176:177], v[174:175], 0, v[176:177]
	v_lshlrev_b64 v[178:179], 15, v[178:179]
	s_lshl_b32 s0, s0, 10
	global_load_lds_dwordx4 v[176:177], off
	v_lshl_add_u64 v[174:175], v[174:175], 0, v[178:179]
	s_add_i32 m0, s8, s0
	v_lshl_add_u64 v[178:179], v[176:177], 0, 64
	global_load_lds_dwordx4 v[174:175], off
	s_add_i32 m0, s31, s3
	v_mfma_f32_16x16x32_f16 v[160:163], v[218:221], v[186:189], v[182:185]
	global_load_lds_dwordx4 v[178:179], off
	v_lshl_add_u64 v[178:179], v[174:175], 0, 64
	s_add_i32 m0, s31, s0
	v_mfma_f32_16x16x32_f16 v[156:159], v[190:193], v[198:201], v[146:149]
	global_load_lds_dwordx4 v[178:179], off
	v_lshl_add_u64 v[178:179], v[176:177], 0, s[24:25]
	s_add_i32 m0, s33, s3
	v_lshl_add_u64 v[176:177], v[176:177], 0, s[46:47]
	global_load_lds_dwordx4 v[178:179], off
	v_lshl_add_u64 v[178:179], v[174:175], 0, s[24:25]
	s_add_i32 m0, s33, s0
	v_mfma_f32_16x16x32_f16 v[148:151], v[190:193], v[206:209], v[210:213]
	global_load_lds_dwordx4 v[178:179], off
	s_add_i32 m0, s35, s3
	v_mfma_f32_16x16x32_f16 v[152:155], v[218:221], v[198:201], v[194:197]
	global_load_lds_dwordx4 v[176:177], off
	s_add_i32 m0, s35, s0
	s_and_b32 s0, s2, 0x60
	s_lshl_b32 s2, s18, 4
	s_andn2_b32 s2, s2, 63
	v_and_or_b32 v187, v169, 15, s2
	v_and_or_b32 v177, v180, 12, s0
	v_sub_u32_e32 v178, v187, v177
	v_cvt_f32_u32_e32 v179, v178
	v_or_b32_e32 v181, 1, v177
	v_sub_u32_e32 v186, v187, v181
	v_cmp_lt_i32_e32 vcc, -1, v178
	v_mul_f32_e32 v179, s9, v179
	v_exp_f32_e32 v192, v179
	v_cvt_f32_u32_e32 v179, v186
	v_or_b32_e32 v180, 2, v177
	v_sub_u32_e32 v188, v187, v180
	v_mul_f32_e32 v164, v164, v192
	v_cndmask_b32_e32 v178, 0, v164, vcc
	v_mul_f32_e32 v164, s9, v179
	v_or_b32_e32 v179, 3, v177
	v_sub_u32_e32 v189, v187, v179
	v_cvt_f32_u32_e32 v184, v188
	v_cvt_f32_u32_e32 v185, v189
	v_exp_f32_e32 v164, v164
	v_cmp_lt_i32_e64 s[38:39], -1, v186
	v_mul_f32_e32 v184, s9, v184
	v_mul_f32_e32 v185, s9, v185
	v_exp_f32_e32 v184, v184
	v_exp_f32_e32 v185, v185
	v_mul_f32_e32 v164, v165, v164
	v_cndmask_b32_e64 v186, 0, v164, s[38:39]
	v_cmp_lt_i32_e64 s[38:39], -1, v188
	v_pk_mul_f32 v[164:165], v[166:167], v[184:185]
	v_or_b32_e32 v167, 16, v177
	v_cvt_pk_f16_f32 v164, v164, v165
	v_cndmask_b32_e64 v165, 0, v164, s[38:39]
	v_lshrrev_b32_e32 v164, 16, v164
	v_cmp_lt_i32_e64 s[38:39], -1, v189
	v_sub_u32_e32 v193, v187, v167
	v_cvt_f32_u32_e32 v166, v193
	v_cndmask_b32_e64 v164, 0, v164, s[38:39]
	v_perm_b32 v185, v164, v165, s53
	v_or_b32_e32 v165, 17, v177
	v_sub_u32_e32 v194, v187, v165
	v_cvt_pk_f16_f32 v184, v178, v186
	v_cvt_f32_u32_e32 v178, v194
	v_mul_f32_e32 v166, s9, v166
	v_exp_f32_e32 v186, v166
	v_or_b32_e32 v166, 19, v177
	v_mul_f32_e32 v188, s9, v178
	v_or_b32_e32 v178, 18, v177
	v_sub_u32_e32 v195, v187, v178
	v_sub_u32_e32 v196, v187, v166
	v_cvt_f32_u32_e32 v189, v195
	v_cvt_f32_u32_e32 v197, v196
	v_lshl_add_u64 v[174:175], v[174:175], 0, s[46:47]
	global_load_lds_dwordx4 v[174:175], off
	v_mul_lo_u32 v174, v187, s7
	v_or_b32_e32 v191, 16, v187
	v_or_b32_e32 v182, 32, v187
	v_or_b32_e32 v175, 48, v187
	v_exp_f32_e32 v187, v188
	v_mul_f32_e32 v188, s9, v189
	v_mul_f32_e32 v189, s9, v197
	v_exp_f32_e32 v188, v188
	v_exp_f32_e32 v189, v189
	v_pk_mul_f32 v[160:161], v[160:161], v[186:187]
	v_cmp_lt_i32_e64 s[38:39], -1, v193
	v_cvt_pk_f16_f32 v160, v160, v161
	v_add_u32_e32 v190, 0, v174
	v_lshlrev_b32_e32 v164, 1, v177
	v_cndmask_b32_e64 v161, 0, v160, s[38:39]
	v_lshrrev_b32_e32 v160, 16, v160
	v_cmp_lt_i32_e64 s[38:39], -1, v194
	v_add_u32_e32 v197, v190, v164
	v_pk_mul_f32 v[162:163], v[162:163], v[188:189]
	v_cndmask_b32_e64 v160, 0, v160, s[38:39]
	ds_write_b64 v197, v[184:185]
	v_perm_b32 v184, v160, v161, s53
	v_cvt_pk_f16_f32 v160, v162, v163
	v_cmp_lt_i32_e64 s[38:39], -1, v195
	v_sub_u32_e32 v188, v191, v181
	v_cvt_f32_u32_e32 v163, v188
	v_cndmask_b32_e64 v161, 0, v160, s[38:39]
	v_lshrrev_b32_e32 v160, 16, v160
	v_cmp_lt_i32_e64 s[38:39], -1, v196
	v_sub_u32_e32 v189, v191, v180
	v_sub_u32_e32 v193, v191, v179
	v_cndmask_b32_e64 v160, 0, v160, s[38:39]
	v_perm_b32 v185, v160, v161, s53
	v_sub_u32_e32 v161, v191, v177
	v_cvt_f32_u32_e32 v162, v161
	v_cvt_f32_u32_e32 v186, v189
	v_cvt_f32_u32_e32 v187, v193
	v_mul_f32_e32 v163, s9, v163
	v_mul_f32_e32 v162, s9, v162
	v_exp_f32_e32 v162, v162
	v_exp_f32_e32 v163, v163
	v_mul_f32_e32 v186, s9, v186
	v_mul_f32_e32 v187, s9, v187
	v_exp_f32_e32 v186, v186
	v_exp_f32_e32 v187, v187
	v_pk_mul_f32 v[156:157], v[156:157], v[162:163]
	v_cmp_lt_i32_e64 s[38:39], -1, v161
	v_cvt_pk_f16_f32 v156, v156, v157
	v_pk_mul_f32 v[158:159], v[158:159], v[186:187]
	v_cndmask_b32_e64 v157, 0, v156, s[38:39]
	v_lshrrev_b32_e32 v156, 16, v156
	v_cmp_lt_i32_e64 s[38:39], -1, v188
	v_add_u32_e32 v183, 0x1100, v190
	v_mul_f32_e32 v152, v152, v192
	v_cndmask_b32_e64 v156, 0, v156, s[38:39]
	v_perm_b32 v156, v156, v157, s53
	v_cvt_pk_f16_f32 v157, v158, v159
	v_sub_u32_e32 v159, v191, v165
	v_cmp_lt_i32_e64 s[38:39], -1, v189
	v_cvt_f32_u32_e32 v161, v159
	v_sub_u32_e32 v162, v191, v166
	v_cndmask_b32_e64 v158, 0, v157, s[38:39]
	v_lshrrev_b32_e32 v157, 16, v157
	v_cmp_lt_i32_e64 s[38:39], -1, v193
	v_lshlrev_b32_e32 v160, 1, v167
	v_add_u32_e32 v163, v183, v160
	v_cndmask_b32_e64 v157, 0, v157, s[38:39]
	v_perm_b32 v157, v157, v158, s53
	v_add_u32_e32 v158, v183, v164
	ds_write_b64 v158, v[156:157]
	v_cndmask_b32_e32 v158, 0, v152, vcc
	v_mul_f32_e32 v152, s9, v161
	v_sub_u32_e32 v161, v191, v178
	v_cvt_f32_u32_e32 v156, v161
	v_cvt_f32_u32_e32 v157, v162
	v_exp_f32_e32 v152, v152
	v_cmp_lt_i32_e32 vcc, -1, v159
	v_mul_f32_e32 v156, s9, v156
	v_mul_f32_e32 v157, s9, v157
	v_exp_f32_e32 v156, v156
	v_exp_f32_e32 v157, v157
	v_mul_f32_e32 v152, v153, v152
	v_cndmask_b32_e32 v159, 0, v152, vcc
	v_cmp_lt_i32_e32 vcc, -1, v161
	v_pk_mul_f32 v[152:153], v[154:155], v[156:157]
	v_cvt_pk_f16_f32 v154, v158, v159
	v_sub_u32_e32 v158, v182, v177
	v_sub_u32_e32 v159, v182, v181
	v_cvt_f32_u32_e32 v156, v158
	v_cvt_f32_u32_e32 v157, v159
	v_cvt_pk_f16_f32 v152, v152, v153
	v_cndmask_b32_e32 v153, 0, v152, vcc
	v_lshrrev_b32_e32 v152, 16, v152
	v_cmp_lt_i32_e32 vcc, -1, v162
	v_sub_u32_e32 v161, v182, v180
	v_sub_u32_e32 v162, v182, v179
	v_cndmask_b32_e32 v152, 0, v152, vcc
	v_perm_b32 v155, v152, v153, s53
	v_mul_f32_e32 v152, s9, v156
	v_mul_f32_e32 v153, s9, v157
	v_cvt_f32_u32_e32 v156, v161
	v_cvt_f32_u32_e32 v157, v162
	v_exp_f32_e32 v152, v152
	v_exp_f32_e32 v153, v153
	v_mul_f32_e32 v156, s9, v156
	v_mul_f32_e32 v157, s9, v157
	v_exp_f32_e32 v156, v156
	v_exp_f32_e32 v157, v157
	v_pk_mul_f32 v[148:149], v[148:149], v[152:153]
	v_cmp_lt_i32_e32 vcc, -1, v158
	v_cvt_pk_f16_f32 v148, v148, v149
	ds_write_b64 v163, v[154:155]
	v_cndmask_b32_e32 v149, 0, v148, vcc
	v_lshrrev_b32_e32 v148, 16, v148
	v_cmp_lt_i32_e32 vcc, -1, v159
	v_pk_mul_f32 v[150:151], v[150:151], v[156:157]
	v_sub_u32_e32 v154, v182, v167
	v_cndmask_b32_e32 v148, 0, v148, vcc
	v_sub_u32_e32 v155, v182, v165
	v_perm_b32 v148, v148, v149, s53
	v_cvt_pk_f16_f32 v149, v150, v151
	v_cvt_f32_u32_e32 v151, v154
	v_cvt_f32_u32_e32 v152, v155
	v_cmp_lt_i32_e32 vcc, -1, v161
	v_sub_u32_e32 v156, v182, v178
	v_sub_u32_e32 v157, v182, v166
	v_cndmask_b32_e32 v150, 0, v149, vcc
	v_lshrrev_b32_e32 v149, 16, v149
	v_cmp_lt_i32_e32 vcc, -1, v162
	v_cvt_f32_u32_e32 v153, v157
	v_mfma_f32_16x16x32_f16 v[144:147], v[218:221], v[206:209], v[202:205]
	v_cndmask_b32_e32 v149, 0, v149, vcc
	v_perm_b32 v149, v149, v150, s53
	v_mul_f32_e32 v150, s9, v151
	v_mul_f32_e32 v151, s9, v152
	v_cvt_f32_u32_e32 v152, v156
	v_exp_f32_e32 v150, v150
	v_exp_f32_e32 v151, v151
	v_mul_f32_e32 v153, s9, v153
	v_mul_f32_e32 v152, s9, v152
	v_exp_f32_e32 v152, v152
	v_exp_f32_e32 v153, v153
	v_pk_mul_f32 v[144:145], v[144:145], v[150:151]
	v_cmp_lt_i32_e32 vcc, -1, v154
	v_cvt_pk_f16_f32 v144, v144, v145
	v_add_u32_e32 v176, 0x2200, v190
	v_cndmask_b32_e32 v145, 0, v144, vcc
	v_lshrrev_b32_e32 v144, 16, v144
	v_cmp_lt_i32_e32 vcc, -1, v155
	v_add_u32_e32 v158, v176, v164
	v_pk_mul_f32 v[146:147], v[146:147], v[152:153]
	v_cndmask_b32_e32 v144, 0, v144, vcc
	v_sub_u32_e32 v150, v175, v177
	v_sub_u32_e32 v151, v175, v181
	ds_write_b64 v158, v[148:149]
	v_perm_b32 v144, v144, v145, s53
	v_cvt_pk_f16_f32 v145, v146, v147
	v_cvt_f32_u32_e32 v147, v150
	v_cvt_f32_u32_e32 v148, v151
	v_cmp_lt_i32_e32 vcc, -1, v156
	v_sub_u32_e32 v152, v175, v180
	v_sub_u32_e32 v153, v175, v179
	v_cndmask_b32_e32 v146, 0, v145, vcc
	v_lshrrev_b32_e32 v145, 16, v145
	v_cmp_lt_i32_e32 vcc, -1, v157
	v_cvt_f32_u32_e32 v149, v153
	v_add_u32_e32 v154, v176, v160
	v_cndmask_b32_e32 v145, 0, v145, vcc
	v_perm_b32 v145, v145, v146, s53
	v_mul_f32_e32 v146, s9, v147
	v_mul_f32_e32 v147, s9, v148
	v_cvt_f32_u32_e32 v148, v152
	v_exp_f32_e32 v146, v146
	v_exp_f32_e32 v147, v147
	v_mul_f32_e32 v149, s9, v149
	v_mul_f32_e32 v148, s9, v148
	v_exp_f32_e32 v148, v148
	v_exp_f32_e32 v149, v149
	v_pk_mul_f32 v[140:141], v[140:141], v[146:147]
	v_cmp_lt_i32_e32 vcc, -1, v150
	v_cvt_pk_f16_f32 v140, v140, v141
	v_pk_mul_f32 v[142:143], v[142:143], v[148:149]
	v_cndmask_b32_e32 v141, 0, v140, vcc
	v_lshrrev_b32_e32 v140, 16, v140
	v_cmp_lt_i32_e32 vcc, -1, v151
	v_sub_u32_e32 v146, v175, v167
	v_sub_u32_e32 v147, v175, v165
	v_cndmask_b32_e32 v140, 0, v140, vcc
	ds_write_b64 v154, v[144:145]
	v_perm_b32 v140, v140, v141, s53
	v_cvt_pk_f16_f32 v141, v142, v143
	v_cvt_f32_u32_e32 v143, v146
	v_cvt_f32_u32_e32 v144, v147
	v_cmp_lt_i32_e32 vcc, -1, v152
	v_sub_u32_e32 v148, v175, v178
	v_sub_u32_e32 v149, v175, v166
	v_cndmask_b32_e32 v142, 0, v141, vcc
	v_lshrrev_b32_e32 v141, 16, v141
	v_cmp_lt_i32_e32 vcc, -1, v153
	v_cvt_f32_u32_e32 v145, v149
	v_add_u32_e32 v174, 0x3300, v190
	v_cndmask_b32_e32 v141, 0, v141, vcc
	v_perm_b32 v141, v141, v142, s53
	v_mul_f32_e32 v142, s9, v143
	v_mul_f32_e32 v143, s9, v144
	v_cvt_f32_u32_e32 v144, v148
	v_exp_f32_e32 v142, v142
	v_exp_f32_e32 v143, v143
	v_mul_f32_e32 v145, s9, v145
	v_mul_f32_e32 v144, s9, v144
	v_exp_f32_e32 v144, v144
	v_exp_f32_e32 v145, v145
	v_pk_mul_f32 v[136:137], v[136:137], v[142:143]
	v_cmp_lt_i32_e32 vcc, -1, v146
	v_cvt_pk_f16_f32 v136, v136, v137
	v_pk_mul_f32 v[138:139], v[138:139], v[144:145]
	v_cndmask_b32_e32 v137, 0, v136, vcc
	v_lshrrev_b32_e32 v136, 16, v136
	v_cmp_lt_i32_e32 vcc, -1, v147
	v_add_u32_e32 v190, v190, v160
	v_add_u32_e32 v150, v174, v164
	v_cndmask_b32_e32 v136, 0, v136, vcc
	v_perm_b32 v136, v136, v137, s53
	v_cvt_pk_f16_f32 v137, v138, v139
	v_cmp_lt_i32_e32 vcc, -1, v148
	ds_write_b64 v190, v[184:185]
	ds_write_b64 v150, v[140:141]
	v_cndmask_b32_e32 v138, 0, v137, vcc
	v_lshrrev_b32_e32 v137, 16, v137
	v_cmp_lt_i32_e32 vcc, -1, v149
	v_add_u32_e32 v144, 49, v171
	v_cvt_f32_i32_e32 v149, v144
	v_cndmask_b32_e32 v137, 0, v137, vcc
	v_perm_b32 v137, v137, v138, s53
	v_add_u32_e32 v138, v174, v160
	ds_write_b64 v138, v[136:137]
	s_waitcnt vmcnt(6) lgkmcnt(0)
	s_barrier
	s_lshl_b32 s2, s18, 6
	v_lshrrev_b32_e32 v153, 4, v169
	v_lshrrev_b32_e32 v137, 2, v169
	v_and_b32_e32 v140, 15, v169
	s_and_b32 s2, s2, 0xc0
	v_xor_b32_e32 v137, v153, v137
	v_or_b32_e32 v136, s2, v140
	v_lshlrev_b32_e32 v137, 4, v137
	v_and_b32_e32 v137, 48, v137
	v_lshlrev_b32_e32 v136, 6, v136
	s_lshl_b32 s0, s18, 4
	v_add3_u32 v154, s8, v137, v136
	s_and_b32 s0, s0, 0xfffffc0
	ds_read_b128 v[136:139], v154
	v_or_b32_e32 v140, s0, v140
	v_and_b32_e32 v141, 48, v169
	v_mul_lo_u32 v140, v140, s7
	v_add3_u32 v148, 0, v141, v140
	v_mul_f32_e32 v152, s9, v149
	ds_read_b128 v[140:143], v148
	ds_read_b128 v[124:127], v148 offset:4352
	ds_read_b128 v[132:135], v154 offset:1024
	ds_read_b128 v[144:147], v148 offset:8704
	ds_read_b128 v[148:151], v148 offset:13056
	v_exp_f32_e32 v152, v152
	v_pk_mul_f32 v[54:55], v[168:169], v[54:55] op_sel_hi:[0,1]
	v_pk_mul_f32 v[52:53], v[168:169], v[52:53] op_sel_hi:[0,1]
	s_waitcnt lgkmcnt(0)
	v_mfma_f32_16x16x32_f16 v[120:123], v[136:139], v[140:143], v[120:123]
	v_mul_f32_e64 v46, v46, v152
	v_mul_f32_e64 v47, v47, v152
	v_pk_mul_f32 v[44:45], v[44:45], v[152:153] op_sel_hi:[1,0]
	v_pk_mul_f32 v[30:31], v[152:153], v[30:31] op_sel_hi:[0,1]
	v_pk_mul_f32 v[28:29], v[152:153], v[28:29] op_sel_hi:[0,1]
	v_mfma_f32_16x16x32_f16 v[116:119], v[136:139], v[124:127], v[116:119]
	v_mul_f32_e64 v20, v170, v20
	v_mul_f32_e64 v21, v170, v21
	v_pk_mul_f32 v[26:27], v[168:169], v[26:27] op_sel_hi:[0,1]
	v_pk_mul_f32 v[24:25], v[168:169], v[24:25] op_sel_hi:[0,1]
	v_mfma_f32_16x16x32_f16 v[48:51], v[136:139], v[144:147], v[48:51]
	v_mul_f32_e64 v10, v170, v10
	v_mul_f32_e64 v11, v170, v11
	v_pk_mul_f32 v[8:9], v[170:171], v[8:9] op_sel_hi:[0,1]
	v_pk_mul_f32 v[6:7], v[172:173], v[6:7] op_sel_hi:[0,1]
	v_mfma_f32_16x16x32_f16 v[44:47], v[136:139], v[148:151], v[44:47]
	ds_read_b128 v[136:139], v154 offset:2048
	v_pk_mul_f32 v[4:5], v[172:173], v[4:5] op_sel_hi:[0,1]
	v_pk_mul_f32 v[2:3], v[152:153], v[2:3] op_sel_hi:[0,1]
	v_mfma_f32_16x16x32_f16 v[52:55], v[132:135], v[140:143], v[52:55]
	v_mul_f32_e64 v0, v152, v0
	v_mul_f32_e64 v1, v152, v1
	s_or_b32 s0, s34, 0x100
	s_lshl_b32 s3, s18, 5
	v_mfma_f32_16x16x32_f16 v[40:43], v[132:135], v[124:127], v[40:43]
	s_add_i32 s3, s3, s0
	s_lshl_b32 s2, s18, 1
	s_or_b32 s2, s2, 1
	v_mfma_f32_16x16x32_f16 v[36:39], v[132:135], v[144:147], v[36:39]
	v_mul_f32_e64 v34, v168, v34
	v_mul_f32_e64 v35, v168, v35
	v_pk_mul_f32 v[32:33], v[168:169], v[32:33] op_sel_hi:[0,1]
	v_pk_mul_f32 v[14:15], v[152:153], v[14:15] op_sel_hi:[0,1]
	v_mfma_f32_16x16x32_f16 v[28:31], v[132:135], v[148:151], v[28:31]
	ds_read_b128 v[132:135], v154 offset:3072
	v_pk_mul_f32 v[12:13], v[152:153], v[12:13] op_sel_hi:[0,1]
	v_pk_mul_f32 v[18:19], v[172:173], v[18:19] op_sel_hi:[0,1]
	s_waitcnt lgkmcnt(0)
	v_mfma_f32_16x16x32_f16 v[20:23], v[136:139], v[124:127], v[20:23]
	v_mul_f32_e64 v16, v172, v16
	v_mul_f32_e64 v17, v172, v17
	v_mfma_f32_16x16x32_f16 v[24:27], v[132:135], v[140:143], v[24:27]
	v_mfma_f32_16x16x32_f16 v[8:11], v[132:135], v[124:127], v[8:11]
	v_xor_b32_e32 v124, v153, v169
	v_lshlrev_b32_e32 v124, 4, v124
	v_and_b32_e32 v224, 48, v124
	v_mfma_f32_16x16x32_f16 v[4:7], v[132:135], v[144:147], v[4:7]
	v_lshl_add_u64 v[124:125], s[16:17], 0, v[224:225]
	v_mfma_f32_16x16x32_f16 v[0:3], v[132:135], v[148:151], v[0:3]
	v_bfe_u32 v132, v169, 2, 4
	v_or_b32_e32 v126, s3, v132
	v_ashrrev_i32_e32 v127, 31, v126
	v_lshlrev_b64 v[126:127], 15, v[126:127]
	s_lshl_b32 s3, s18, 11
	v_lshl_add_u64 v[126:127], v[124:125], 0, v[126:127]
	s_add_i32 m0, s30, s3
	v_mfma_f32_16x16x32_f16 v[12:15], v[136:139], v[148:151], v[12:15]
	global_load_lds_dwordx4 v[126:127], off
	v_or_b32_e32 v126, s0, v132
	v_lshl_add_u32 v126, s2, 4, v126
	v_ashrrev_i32_e32 v127, 31, v126
	v_lshlrev_b64 v[126:127], 15, v[126:127]
	s_lshl_b32 s2, s2, 10
	v_lshl_add_u64 v[124:125], v[124:125], 0, v[126:127]
	s_add_i32 m0, s30, s2
	v_mfma_f32_16x16x32_f16 v[32:35], v[136:139], v[140:143], v[32:35]
	global_load_lds_dwordx4 v[124:125], off
	s_waitcnt vmcnt(6) lgkmcnt(0)
	s_barrier
	s_lshl_b32 s3, s18, 6
	v_lshrrev_b32_e32 v152, 4, v169
	v_lshrrev_b32_e32 v125, 2, v169
	v_and_b32_e32 v132, 15, v169
	s_and_b32 s3, s3, 0xc0
	v_xor_b32_e32 v125, v152, v125
	v_or_b32_e32 v124, s3, v132
	v_lshlrev_b32_e32 v125, 4, v125
	v_and_b32_e32 v125, 48, v125
	v_lshlrev_b32_e32 v124, 6, v124
	s_lshl_b32 s2, s18, 4
	v_add3_u32 v153, s31, v125, v124
	s_and_b32 s2, s2, 0xfffffc0
	ds_read_b128 v[124:127], v153
	v_or_b32_e32 v132, s2, v132
	v_and_b32_e32 v133, 48, v169
	v_mul_lo_u32 v132, v132, s7
	v_add3_u32 v148, 0, v133, v132
	v_mfma_f32_16x16x32_f16 v[16:19], v[136:139], v[144:147], v[16:19]
	ds_read_b128 v[132:135], v148 offset:64
	ds_read_b128 v[136:139], v148 offset:4416
	ds_read_b128 v[140:143], v153 offset:1024
	ds_read_b128 v[144:147], v148 offset:8768
	ds_read_b128 v[148:151], v148 offset:13120
	s_lshl_b32 s3, s18, 5
	s_waitcnt lgkmcnt(0)
	v_mfma_f32_16x16x32_f16 v[120:123], v[124:127], v[132:135], v[120:123]
	s_add_i32 s3, s3, s0
	s_lshl_b32 s2, s18, 1
	s_or_b32 s2, s2, 1
	v_mfma_f32_16x16x32_f16 v[116:119], v[124:127], v[136:139], v[116:119]
	v_mfma_f32_16x16x32_f16 v[48:51], v[124:127], v[144:147], v[48:51]
	v_mfma_f32_16x16x32_f16 v[44:47], v[124:127], v[148:151], v[44:47]
	v_mfma_f32_16x16x32_f16 v[52:55], v[140:143], v[132:135], v[52:55]
	v_mfma_f32_16x16x32_f16 v[40:43], v[140:143], v[136:139], v[40:43]
	v_mfma_f32_16x16x32_f16 v[36:39], v[140:143], v[144:147], v[36:39]
	v_mfma_f32_16x16x32_f16 v[28:31], v[140:143], v[148:151], v[28:31]
	ds_read_b128 v[124:127], v153 offset:2048
	ds_read_b128 v[140:143], v153 offset:3072
	s_waitcnt lgkmcnt(0)
	v_mfma_f32_16x16x32_f16 v[32:35], v[124:127], v[132:135], v[32:35]
	v_mfma_f32_16x16x32_f16 v[20:23], v[124:127], v[136:139], v[20:23]
	v_mfma_f32_16x16x32_f16 v[16:19], v[124:127], v[144:147], v[16:19]
	v_mfma_f32_16x16x32_f16 v[12:15], v[124:127], v[148:151], v[12:15]
	v_xor_b32_e32 v124, v152, v169
	v_lshlrev_b32_e32 v124, 4, v124
	v_and_b32_e32 v224, 48, v124
	v_mfma_f32_16x16x32_f16 v[24:27], v[140:143], v[132:135], v[24:27]
	v_bfe_u32 v132, v169, 2, 4
	v_or_b32_e32 v126, s3, v132
	v_ashrrev_i32_e32 v127, 31, v126
	v_lshl_add_u64 v[124:125], s[16:17], 0, v[224:225]
	v_lshlrev_b64 v[126:127], 15, v[126:127]
	v_lshl_add_u64 v[126:127], v[124:125], 0, v[126:127]
	s_lshl_b32 s3, s18, 11
	v_lshl_add_u64 v[126:127], v[126:127], 0, 64
	s_add_i32 m0, s8, s3
	v_mfma_f32_16x16x32_f16 v[0:3], v[140:143], v[148:151], v[0:3]
	global_load_lds_dwordx4 v[126:127], off
	v_or_b32_e32 v126, s0, v132
	v_lshl_add_u32 v126, s2, 4, v126
	v_ashrrev_i32_e32 v127, 31, v126
	v_lshlrev_b64 v[126:127], 15, v[126:127]
	v_lshl_add_u64 v[124:125], v[124:125], 0, v[126:127]
	s_lshl_b32 s2, s2, 10
	v_lshl_add_u64 v[124:125], v[124:125], 0, 64
	s_add_i32 m0, s8, s2
	v_mfma_f32_16x16x32_f16 v[8:11], v[140:143], v[136:139], v[8:11]
	global_load_lds_dwordx4 v[124:125], off
	s_waitcnt vmcnt(6) lgkmcnt(0)
	s_barrier
	s_lshl_b32 s2, s18, 4
	v_lshrrev_b32_e32 v168, 4, v169
	s_lshl_b32 s3, s18, 6
	v_lshrrev_b32_e32 v125, 2, v169
	v_and_b32_e32 v132, 15, v169
	s_and_b32 s2, s2, 0xfffffc0
	s_and_b32 s3, s3, 0xc0
	v_xor_b32_e32 v125, v168, v125
	v_or_b32_e32 v124, s3, v132
	v_lshlrev_b32_e32 v125, 4, v125
	v_or_b32_e32 v132, s2, v132
	v_and_b32_e32 v133, 48, v169
	v_and_b32_e32 v125, 48, v125
	v_lshlrev_b32_e32 v124, 6, v124
	v_mul_lo_u32 v132, v132, s7
	v_add3_u32 v160, s33, v125, v124
	v_add3_u32 v148, 0, v133, v132
	v_mfma_f32_16x16x32_f16 v[4:7], v[140:143], v[144:147], v[4:7]
	ds_read_b128 v[124:127], v160
	ds_read_b128 v[132:135], v148 offset:128
	ds_read_b128 v[136:139], v148 offset:4480
	ds_read_b128 v[140:143], v160 offset:1024
	ds_read_b128 v[144:147], v148 offset:8832
	ds_read_b128 v[148:151], v148 offset:13184
	s_waitcnt lgkmcnt(0)
	v_mfma_f32_16x16x32_f16 v[152:155], v[140:143], v[136:139], v[40:43]
	s_lshl_b32 s3, s18, 5
	s_add_i32 s3, s3, s0
	s_lshl_b32 s2, s18, 1
	v_mfma_f32_16x16x32_f16 v[156:159], v[140:143], v[144:147], v[36:39]
	s_nop 2
	ds_read_b128 v[36:39], v160 offset:2048
	ds_read_b128 v[40:43], v160 offset:3072
	s_or_b32 s2, s2, 1
	v_mfma_f32_16x16x32_f16 v[48:51], v[124:127], v[144:147], v[48:51]
	s_waitcnt lgkmcnt(0)
	v_mfma_f32_16x16x32_f16 v[16:19], v[36:39], v[144:147], v[16:19]
	v_mfma_f32_16x16x32_f16 v[160:163], v[36:39], v[148:151], v[12:15]
	v_mfma_f32_16x16x32_f16 v[144:147], v[40:43], v[144:147], v[4:7]
	v_mfma_f32_16x16x32_f16 v[12:15], v[40:43], v[148:151], v[0:3]
	s_nop 1
	v_bfe_u32 v4, v169, 2, 4
	v_xor_b32_e32 v0, v168, v169
	v_lshlrev_b32_e32 v0, 4, v0
	v_or_b32_e32 v2, s3, v4
	v_and_b32_e32 v224, 48, v0
	v_ashrrev_i32_e32 v3, 31, v2
	v_lshl_add_u64 v[0:1], s[16:17], 0, v[224:225]
	v_lshlrev_b64 v[2:3], 15, v[2:3]
	v_lshl_add_u64 v[2:3], v[0:1], 0, v[2:3]
	s_lshl_b32 s3, s18, 11
	v_lshl_add_u64 v[2:3], v[2:3], 0, s[24:25]
	s_add_i32 m0, s31, s3
	v_mfma_f32_16x16x32_f16 v[120:123], v[124:127], v[132:135], v[120:123]
	global_load_lds_dwordx4 v[2:3], off
	v_or_b32_e32 v2, s0, v4
	v_lshl_add_u32 v2, s2, 4, v2
	v_ashrrev_i32_e32 v3, 31, v2
	v_lshlrev_b64 v[2:3], 15, v[2:3]
	v_lshl_add_u64 v[0:1], v[0:1], 0, v[2:3]
	s_lshl_b32 s2, s2, 10
	v_lshl_add_u64 v[0:1], v[0:1], 0, s[24:25]
	s_add_i32 m0, s31, s2
	v_mfma_f32_16x16x32_f16 v[52:55], v[140:143], v[132:135], v[52:55]
	global_load_lds_dwordx4 v[0:1], off
	s_waitcnt vmcnt(6) lgkmcnt(0)
	v_mfma_f32_16x16x32_f16 v[32:35], v[36:39], v[132:135], v[32:35]
	s_barrier
	v_mfma_f32_16x16x32_f16 v[164:167], v[40:43], v[132:135], v[24:27]
	s_lshl_b32 s3, s18, 6
	v_lshrrev_b32_e32 v133, 4, v169
	v_lshrrev_b32_e32 v1, 2, v169
	v_and_b32_e32 v4, 15, v169
	s_and_b32 s3, s3, 0xc0
	v_xor_b32_e32 v1, v133, v1
	v_or_b32_e32 v0, s3, v4
	v_lshlrev_b32_e32 v1, 4, v1
	v_and_b32_e32 v1, 48, v1
	v_lshlrev_b32_e32 v0, 6, v0
	s_lshl_b32 s2, s18, 4
	v_add3_u32 v132, s35, v1, v0
	s_and_b32 s2, s2, 0xfffffc0
	ds_read_b128 v[0:3], v132
	v_or_b32_e32 v4, s2, v4
	v_and_b32_e32 v5, 48, v169
	v_mul_lo_u32 v4, v4, s7
	v_mfma_f32_16x16x32_f16 v[116:119], v[124:127], v[136:139], v[116:119]
	s_lshl_b32 s3, s18, 5
	s_add_i32 s3, s3, s0
	s_lshl_b32 s2, s18, 1
	v_mfma_f32_16x16x32_f16 v[28:31], v[140:143], v[148:151], v[28:31]
	s_or_b32 s2, s2, 1
	v_mfma_f32_16x16x32_f16 v[140:143], v[36:39], v[136:139], v[20:23]
	v_mfma_f32_16x16x32_f16 v[136:139], v[40:43], v[136:139], v[8:11]
	s_nop 2
	v_add3_u32 v8, 0, v5, v4
	v_mfma_f32_16x16x32_f16 v[44:47], v[124:127], v[148:151], v[44:47]
	ds_read_b128 v[148:151], v8 offset:192
	ds_read_b128 v[174:177], v8 offset:4544
	ds_read_b128 v[4:7], v132 offset:1024
	ds_read_b128 v[178:181], v8 offset:8896
	ds_read_b128 v[182:185], v8 offset:13248
	s_waitcnt lgkmcnt(0)
	v_mfma_f32_16x16x32_f16 v[124:127], v[0:3], v[148:151], v[120:123]
	v_mfma_f32_16x16x32_f16 v[40:43], v[0:3], v[174:177], v[116:119]
	v_mfma_f32_16x16x32_f16 v[24:27], v[0:3], v[178:181], v[48:51]
	v_mfma_f32_16x16x32_f16 v[8:11], v[0:3], v[182:185], v[44:47]
	v_mfma_f32_16x16x32_f16 v[0:3], v[4:7], v[182:185], v[28:31]
	s_nop 2
	v_add_u32_e32 v28, 1, v173
	v_cvt_f32_i32_e32 v28, v28
	v_mfma_f32_16x16x32_f16 v[120:123], v[4:7], v[148:151], v[52:55]
	v_mul_f32_e32 v28, s9, v28
	v_exp_f32_e32 v134, v28
	v_add_u32_e32 v28, 17, v173
	v_cvt_f32_i32_e32 v28, v28
	v_mfma_f32_16x16x32_f16 v[36:39], v[4:7], v[174:177], v[152:155]
	v_mul_f32_e64 v54, v110, v134
	v_mul_f32_e64 v55, v111, v134
	v_pk_mul_f32 v[52:53], v[108:109], v[134:135] op_sel_hi:[1,0]
	v_mul_f32_e32 v28, s9, v28
	v_mfma_f32_16x16x32_f16 v[20:23], v[4:7], v[178:181], v[156:159]
	ds_read_b128 v[4:7], v132 offset:2048
	ds_read_b128 v[48:51], v132 offset:3072
	v_exp_f32_e32 v132, v28
	v_add_u32_e32 v28, 33, v173
	s_waitcnt lgkmcnt(0)
	v_mfma_f32_16x16x32_f16 v[116:119], v[4:7], v[148:151], v[32:35]
	v_cvt_f32_i32_e32 v28, v28
	v_mul_f32_e32 v28, s9, v28
	v_mfma_f32_16x16x32_f16 v[32:35], v[4:7], v[174:177], v[140:143]
	s_nop 2
	v_mul_f32_e64 v140, v106, v132
	v_mul_f32_e64 v141, v107, v132
	v_mfma_f32_16x16x32_f16 v[44:47], v[48:51], v[174:177], v[136:139]
	v_xor_b32_e32 v106, v133, v169
	v_lshlrev_b32_e32 v106, 4, v106
	v_and_b32_e32 v224, 48, v106
	v_pk_mul_f32 v[138:139], v[104:105], v[132:133] op_sel_hi:[1,0]
	v_bfe_u32 v105, v169, 2, 4
	v_or_b32_e32 v136, s3, v105
	v_ashrrev_i32_e32 v137, 31, v136
	v_lshl_add_u64 v[106:107], s[16:17], 0, v[224:225]
	v_lshlrev_b64 v[136:137], 15, v[136:137]
	v_lshl_add_u64 v[136:137], v[106:107], 0, v[136:137]
	s_lshl_b32 s3, s18, 11
	v_lshl_add_u64 v[136:137], v[136:137], 0, s[46:47]
	s_add_i32 m0, s33, s3
	v_or_b32_e32 v105, s0, v105
	global_load_lds_dwordx4 v[136:137], off
	v_lshl_add_u32 v136, s2, 4, v105
	v_ashrrev_i32_e32 v137, 31, v136
	v_lshlrev_b64 v[136:137], 15, v[136:137]
	v_lshl_add_u64 v[106:107], v[106:107], 0, v[136:137]
	s_lshl_b32 s2, s2, 10
	v_lshl_add_u64 v[106:107], v[106:107], 0, s[46:47]
	s_add_i32 m0, s33, s2
	v_exp_f32_e32 v104, v28
	global_load_lds_dwordx4 v[106:107], off
	s_waitcnt vmcnt(6) lgkmcnt(0)
	s_barrier
	s_lshl_b32 s3, s18, 6
	v_lshrrev_b32_e32 v133, 4, v169
	v_lshrrev_b32_e32 v135, 2, v169
	v_and_b32_e32 v105, 15, v169
	s_and_b32 s3, s3, 0xc0
	v_xor_b32_e32 v135, v133, v135
	v_or_b32_e32 v107, s3, v105
	v_lshlrev_b32_e32 v135, 4, v135
	v_and_b32_e32 v135, 48, v135
	v_lshlrev_b32_e32 v107, 6, v107
	s_lshl_b32 s2, s18, 4
	v_add3_u32 v107, s30, v135, v107
	v_mfma_f32_16x16x32_f16 v[28:31], v[48:51], v[178:181], v[144:147]
	s_and_b32 s2, s2, 0xfffffc0
	v_or_b32_e32 v105, s2, v105
	v_and_b32_e32 v106, 48, v169
	ds_read_b128 v[142:145], v107
	v_mul_lo_u32 v105, v105, s7
	v_add3_u32 v105, 0, v106, v105
	v_mfma_f32_16x16x32_f16 v[108:111], v[48:51], v[148:151], v[164:167]
	ds_read_b128 v[146:149], v105
	ds_read_b128 v[150:153], v105 offset:4352
	ds_read_b128 v[154:157], v107 offset:1024
	v_pk_mul_f32 v[98:99], v[98:99], v[104:105] op_sel_hi:[1,0]
	v_mfma_f32_16x16x32_f16 v[12:15], v[48:51], v[182:185], v[12:15]
	v_mul_f32_e64 v96, v96, v104
	v_mul_f32_e64 v97, v97, v104
	v_pk_mul_f32 v[102:103], v[134:135], v[102:103] op_sel_hi:[0,1]
	v_pk_mul_f32 v[100:101], v[134:135], v[100:101] op_sel_hi:[0,1]
	s_waitcnt lgkmcnt(0)
	v_mfma_f32_16x16x32_f16 v[48:51], v[142:145], v[146:149], v[52:55]
	v_mul_f32_e64 v90, v132, v90
	v_mul_f32_e64 v91, v132, v91
	v_pk_mul_f32 v[88:89], v[132:133], v[88:89] op_sel_hi:[0,1]
	v_pk_mul_f32 v[86:87], v[104:105], v[86:87] op_sel_hi:[0,1]
	v_add_u32_e32 v52, 49, v173
	v_cvt_f32_i32_e32 v106, v52
	v_mfma_f32_16x16x32_f16 v[16:19], v[4:7], v[178:181], v[16:19]
	v_mul_f32_e64 v84, v104, v84
	v_mul_f32_e64 v85, v104, v85
	s_lshl_b32 s3, s18, 5
	v_mul_f32_e32 v106, s9, v106
	v_mfma_f32_16x16x32_f16 v[4:7], v[4:7], v[182:185], v[160:163]
	v_mul_f32_e64 v70, v132, v70
	v_mul_f32_e64 v71, v132, v71
	v_pk_mul_f32 v[68:69], v[132:133], v[68:69] op_sel_hi:[0,1]
	v_pk_mul_f32 v[66:67], v[104:105], v[66:67] op_sel_hi:[0,1]
	ds_read_b128 v[158:161], v105 offset:8704
	v_mfma_f32_16x16x32_f16 v[52:55], v[142:145], v[150:153], v[138:141]
	v_exp_f32_e32 v162, v106
	v_pk_mul_f32 v[64:65], v[104:105], v[64:65] op_sel_hi:[0,1]
	v_pk_mul_f32 v[58:59], v[132:133], v[58:59] op_sel_hi:[0,1]
	ds_read_b128 v[136:139], v105 offset:13056
	v_pk_mul_f32 v[94:95], v[94:95], v[162:163] op_sel_hi:[1,0]
	v_pk_mul_f32 v[92:93], v[92:93], v[162:163] op_sel_hi:[1,0]
	v_pk_mul_f32 v[78:79], v[162:163], v[78:79] op_sel_hi:[0,1]
	v_pk_mul_f32 v[76:77], v[162:163], v[76:77] op_sel_hi:[0,1]
	s_waitcnt lgkmcnt(0)
	v_mfma_f32_16x16x32_f16 v[96:99], v[142:145], v[158:161], v[96:99]
	v_mul_f32_e64 v56, v132, v56
	v_mul_f32_e64 v57, v132, v57
	v_bfe_u32 v132, v169, 2, 4
	s_add_i32 s3, s3, s0
	v_mfma_f32_16x16x32_f16 v[92:95], v[142:145], v[136:139], v[92:95]
	ds_read_b128 v[140:143], v107 offset:2048
	s_lshl_b32 s2, s18, 1
	s_or_b32 s2, s2, 1
	v_mfma_f32_16x16x32_f16 v[100:103], v[154:157], v[146:149], v[100:103]
	v_mul_f32_e64 v82, v134, v82
	v_mul_f32_e64 v83, v134, v83
	v_pk_mul_f32 v[80:81], v[134:135], v[80:81] op_sel_hi:[0,1]
	v_pk_mul_f32 v[74:75], v[134:135], v[74:75] op_sel_hi:[0,1]
	v_mfma_f32_16x16x32_f16 v[88:91], v[154:157], v[150:153], v[88:91]
	v_mul_f32_e64 v72, v134, v72
	v_mul_f32_e64 v73, v134, v73
	v_pk_mul_f32 v[62:63], v[162:163], v[62:63] op_sel_hi:[0,1]
	v_pk_mul_f32 v[60:61], v[162:163], v[60:61] op_sel_hi:[0,1]
	v_mfma_f32_16x16x32_f16 v[84:87], v[154:157], v[158:161], v[84:87]
	v_mfma_f32_16x16x32_f16 v[76:79], v[154:157], v[136:139], v[76:79]
	ds_read_b128 v[154:157], v107 offset:3072
	v_pk_mul_f32 v[106:107], v[104:105], v[114:115] op_sel_hi:[0,1]
	v_pk_mul_f32 v[104:105], v[104:105], v[112:113] op_sel_hi:[0,1]
	v_pk_mul_f32 v[112:113], v[162:163], v[128:129] op_sel_hi:[0,1]
	v_xor_b32_e32 v128, v133, v169
	v_pk_mul_f32 v[114:115], v[162:163], v[130:131] op_sel_hi:[0,1]
	v_lshlrev_b32_e32 v128, 4, v128
	v_or_b32_e32 v130, s3, v132
	v_and_b32_e32 v224, 48, v128
	v_ashrrev_i32_e32 v131, 31, v130
	v_lshl_add_u64 v[128:129], s[16:17], 0, v[224:225]
	v_lshlrev_b64 v[130:131], 15, v[130:131]
	v_lshl_add_u64 v[130:131], v[128:129], 0, v[130:131]
	s_lshl_b32 s3, s18, 11
	v_lshl_add_u64 v[130:131], v[130:131], 0, s[46:47]
	s_add_i32 m0, s33, s3
	s_waitcnt lgkmcnt(0)
	v_mfma_f32_16x16x32_f16 v[68:71], v[140:143], v[150:153], v[68:71]
	global_load_lds_dwordx4 v[130:131], off
	v_or_b32_e32 v130, s0, v132
	v_lshl_add_u32 v130, s2, 4, v130
	v_ashrrev_i32_e32 v131, 31, v130
	v_lshlrev_b64 v[130:131], 15, v[130:131]
	v_lshl_add_u64 v[128:129], v[128:129], 0, v[130:131]
	s_lshl_b32 s2, s2, 10
	v_lshl_add_u64 v[128:129], v[128:129], 0, s[46:47]
	s_add_i32 m0, s33, s2
	v_mfma_f32_16x16x32_f16 v[56:59], v[154:157], v[150:153], v[56:59]
	global_load_lds_dwordx4 v[128:129], off
	s_waitcnt vmcnt(6) lgkmcnt(0)
	s_barrier
	s_lshl_b32 s3, s18, 6
	v_lshrrev_b32_e32 v152, 4, v169
	v_lshrrev_b32_e32 v129, 2, v169
	v_and_b32_e32 v132, 15, v169
	s_and_b32 s3, s3, 0xc0
	v_xor_b32_e32 v129, v152, v129
	v_or_b32_e32 v128, s3, v132
	v_lshlrev_b32_e32 v129, 4, v129
	v_and_b32_e32 v129, 48, v129
	v_lshlrev_b32_e32 v128, 6, v128
	s_lshl_b32 s2, s18, 4
	v_add3_u32 v153, s8, v129, v128
	s_and_b32 s2, s2, 0xfffffc0
	ds_read_b128 v[128:131], v153
	v_or_b32_e32 v132, s2, v132
	v_and_b32_e32 v133, 48, v169
	v_mul_lo_u32 v132, v132, s7
	v_mfma_f32_16x16x32_f16 v[80:83], v[140:143], v[146:149], v[80:83]
	s_lshl_b32 s3, s18, 5
	s_add_i32 s3, s3, s0
	s_lshl_b32 s2, s18, 1
	v_mfma_f32_16x16x32_f16 v[72:75], v[154:157], v[146:149], v[72:75]
	v_add3_u32 v148, 0, v133, v132
	s_or_b32 s2, s2, 1
	v_mfma_f32_16x16x32_f16 v[64:67], v[140:143], v[158:161], v[64:67]
	v_mfma_f32_16x16x32_f16 v[60:63], v[140:143], v[136:139], v[60:63]
	v_mfma_f32_16x16x32_f16 v[112:115], v[154:157], v[136:139], v[112:115]
	ds_read_b128 v[132:135], v148 offset:64
	ds_read_b128 v[136:139], v148 offset:4416
	ds_read_b128 v[140:143], v153 offset:1024
	ds_read_b128 v[144:147], v148 offset:8768
	ds_read_b128 v[148:151], v148 offset:13120
	s_waitcnt lgkmcnt(0)
	v_mfma_f32_16x16x32_f16 v[48:51], v[128:131], v[132:135], v[48:51]
	v_mfma_f32_16x16x32_f16 v[52:55], v[128:131], v[136:139], v[52:55]
	v_mfma_f32_16x16x32_f16 v[96:99], v[128:131], v[144:147], v[96:99]
	v_mfma_f32_16x16x32_f16 v[92:95], v[128:131], v[148:151], v[92:95]
	v_mfma_f32_16x16x32_f16 v[100:103], v[140:143], v[132:135], v[100:103]
	v_mfma_f32_16x16x32_f16 v[88:91], v[140:143], v[136:139], v[88:91]
	v_mfma_f32_16x16x32_f16 v[84:87], v[140:143], v[144:147], v[84:87]
	v_mfma_f32_16x16x32_f16 v[76:79], v[140:143], v[148:151], v[76:79]
	ds_read_b128 v[128:131], v153 offset:2048
	ds_read_b128 v[140:143], v153 offset:3072
	s_waitcnt lgkmcnt(0)
	v_mfma_f32_16x16x32_f16 v[80:83], v[128:131], v[132:135], v[80:83]
	v_mfma_f32_16x16x32_f16 v[68:71], v[128:131], v[136:139], v[68:71]
	v_mfma_f32_16x16x32_f16 v[64:67], v[128:131], v[144:147], v[64:67]
	v_mfma_f32_16x16x32_f16 v[60:63], v[128:131], v[148:151], v[60:63]
	v_xor_b32_e32 v128, v152, v169
	v_lshlrev_b32_e32 v128, 4, v128
	v_and_b32_e32 v224, 48, v128
	v_mfma_f32_16x16x32_f16 v[72:75], v[140:143], v[132:135], v[72:75]
	v_bfe_u32 v132, v169, 2, 4
	v_or_b32_e32 v130, s3, v132
	v_ashrrev_i32_e32 v131, 31, v130
	v_lshl_add_u64 v[128:129], s[16:17], 0, v[224:225]
	v_lshlrev_b64 v[130:131], 15, v[130:131]
	v_lshl_add_u64 v[130:131], v[128:129], 0, v[130:131]
	s_lshl_b32 s3, s18, 11
	v_lshl_add_u64 v[130:131], v[130:131], 0, s[46:47]
	s_add_i32 m0, s33, s3
	v_mfma_f32_16x16x32_f16 v[104:107], v[154:157], v[158:161], v[104:107]
	global_load_lds_dwordx4 v[130:131], off
	v_or_b32_e32 v130, s0, v132
	v_lshl_add_u32 v130, s2, 4, v130
	v_ashrrev_i32_e32 v131, 31, v130
	v_lshlrev_b64 v[130:131], 15, v[130:131]
	v_lshl_add_u64 v[128:129], v[128:129], 0, v[130:131]
	s_lshl_b32 s2, s2, 10
	v_lshl_add_u64 v[128:129], v[128:129], 0, s[46:47]
	s_add_i32 m0, s33, s2
	v_mfma_f32_16x16x32_f16 v[112:115], v[140:143], v[148:151], v[112:115]
	global_load_lds_dwordx4 v[128:129], off
	s_waitcnt vmcnt(6) lgkmcnt(0)
	s_barrier
	s_lshl_b32 s3, s18, 6
	v_lshrrev_b32_e32 v156, 4, v169
	v_lshrrev_b32_e32 v129, 2, v169
	v_and_b32_e32 v132, 15, v169
	s_and_b32 s3, s3, 0xc0
	v_xor_b32_e32 v129, v156, v129
	v_or_b32_e32 v128, s3, v132
	v_lshlrev_b32_e32 v129, 4, v129
	v_and_b32_e32 v129, 48, v129
	v_lshlrev_b32_e32 v128, 6, v128
	s_lshl_b32 s2, s18, 4
	v_add3_u32 v152, s31, v129, v128
	s_and_b32 s2, s2, 0xfffffc0
	ds_read_b128 v[128:131], v152
	v_or_b32_e32 v132, s2, v132
	v_and_b32_e32 v133, 48, v169
	v_mul_lo_u32 v132, v132, s7
	v_add3_u32 v148, 0, v133, v132
	v_mfma_f32_16x16x32_f16 v[56:59], v[140:143], v[136:139], v[56:59]
	s_lshl_b32 s3, s18, 5
	s_add_i32 s3, s3, s0
	s_lshl_b32 s2, s18, 1
	v_mfma_f32_16x16x32_f16 v[104:107], v[140:143], v[144:147], v[104:107]
	ds_read_b128 v[132:135], v148 offset:128
	ds_read_b128 v[136:139], v148 offset:4480
	ds_read_b128 v[140:143], v152 offset:1024
	ds_read_b128 v[144:147], v148 offset:8832
	ds_read_b128 v[148:151], v148 offset:13184
	s_or_b32 s2, s2, 1
	s_waitcnt lgkmcnt(0)
	v_mfma_f32_16x16x32_f16 v[48:51], v[128:131], v[132:135], v[48:51]
	v_mfma_f32_16x16x32_f16 v[52:55], v[128:131], v[136:139], v[52:55]
	v_mfma_f32_16x16x32_f16 v[96:99], v[128:131], v[144:147], v[96:99]
	v_mfma_f32_16x16x32_f16 v[128:131], v[128:131], v[148:151], v[92:95]
	v_mfma_f32_16x16x32_f16 v[100:103], v[140:143], v[132:135], v[100:103]
	v_mfma_f32_16x16x32_f16 v[88:91], v[140:143], v[136:139], v[88:91]
	v_mfma_f32_16x16x32_f16 v[84:87], v[140:143], v[144:147], v[84:87]
	v_mfma_f32_16x16x32_f16 v[140:143], v[140:143], v[148:151], v[76:79]
	s_nop 2
	ds_read_b128 v[76:79], v152 offset:2048
	ds_read_b128 v[92:95], v152 offset:3072
	s_waitcnt lgkmcnt(0)
	v_mfma_f32_16x16x32_f16 v[80:83], v[76:79], v[132:135], v[80:83]
	v_mfma_f32_16x16x32_f16 v[152:155], v[76:79], v[148:151], v[60:63]
	v_mfma_f32_16x16x32_f16 v[132:135], v[92:95], v[132:135], v[72:75]
	s_nop 1
	v_xor_b32_e32 v60, v156, v169
	v_lshlrev_b32_e32 v60, 4, v60
	v_and_b32_e32 v224, 48, v60
	v_bfe_u32 v72, v169, 2, 4
	v_or_b32_e32 v62, s3, v72
	v_ashrrev_i32_e32 v63, 31, v62
	v_lshl_add_u64 v[60:61], s[16:17], 0, v[224:225]
	v_lshlrev_b64 v[62:63], 15, v[62:63]
	v_lshl_add_u64 v[62:63], v[60:61], 0, v[62:63]
	s_lshl_b32 s3, s18, 11
	v_lshl_add_u64 v[62:63], v[62:63], 0, s[46:47]
	s_add_i32 m0, s33, s3
	v_mfma_f32_16x16x32_f16 v[68:71], v[76:79], v[136:139], v[68:71]
	global_load_lds_dwordx4 v[62:63], off
	v_or_b32_e32 v62, s0, v72
	v_lshl_add_u32 v62, s2, 4, v62
	v_ashrrev_i32_e32 v63, 31, v62
	v_lshlrev_b64 v[62:63], 15, v[62:63]
	v_lshl_add_u64 v[60:61], v[60:61], 0, v[62:63]
	s_lshl_b32 s2, s2, 10
	v_lshl_add_u64 v[60:61], v[60:61], 0, s[46:47]
	s_add_i32 m0, s33, s2
	v_mfma_f32_16x16x32_f16 v[64:67], v[76:79], v[144:147], v[64:67]
	global_load_lds_dwordx4 v[60:61], off
	s_waitcnt vmcnt(6) lgkmcnt(0)
	s_barrier
	s_lshl_b32 s3, s18, 6
	v_lshrrev_b32_e32 v168, 4, v169
	v_lshrrev_b32_e32 v61, 2, v169
	v_and_b32_e32 v72, 15, v169
	s_and_b32 s3, s3, 0xc0
	v_xor_b32_e32 v61, v168, v61
	v_or_b32_e32 v60, s3, v72
	v_lshlrev_b32_e32 v61, 4, v61
	v_and_b32_e32 v61, 48, v61
	v_lshlrev_b32_e32 v60, 6, v60
	s_lshl_b32 s2, s18, 4
	v_add3_u32 v174, s33, v61, v60
	s_and_b32 s2, s2, 0xfffffc0
	ds_read_b128 v[60:63], v174
	v_or_b32_e32 v72, s2, v72
	v_and_b32_e32 v73, 48, v169
	v_mul_lo_u32 v72, v72, s7
	v_add3_u32 v72, 0, v73, v72
	v_mfma_f32_16x16x32_f16 v[56:59], v[92:95], v[136:139], v[56:59]
	s_lshl_b32 s3, s18, 5
	s_add_i32 s3, s3, s0
	s_lshl_b32 s2, s18, 1
	v_mfma_f32_16x16x32_f16 v[136:139], v[92:95], v[144:147], v[104:107]
	s_or_b32 s2, s2, 1
	v_mfma_f32_16x16x32_f16 v[144:147], v[92:95], v[148:151], v[112:115]
	ds_read_b128 v[148:151], v72 offset:192
	ds_read_b128 v[156:159], v72 offset:4544
	ds_read_b128 v[160:163], v174 offset:1024
	ds_read_b128 v[164:167], v72 offset:8896
	ds_read_b128 v[170:173], v72 offset:13248
	s_waitcnt lgkmcnt(0)
	v_mfma_f32_16x16x32_f16 v[112:115], v[60:63], v[148:151], v[48:51]
	v_mfma_f32_16x16x32_f16 v[92:95], v[60:63], v[156:159], v[52:55]
	v_mfma_f32_16x16x32_f16 v[76:79], v[60:63], v[164:167], v[96:99]
	v_mfma_f32_16x16x32_f16 v[60:63], v[60:63], v[170:173], v[128:131]
	ds_read_b128 v[48:51], v174 offset:2048
	s_nop 1
	ds_read_b128 v[128:131], v174 offset:3072
	v_mfma_f32_16x16x32_f16 v[104:107], v[160:163], v[148:151], v[100:103]
	s_waitcnt lgkmcnt(0)
	v_mfma_f32_16x16x32_f16 v[100:103], v[48:51], v[148:151], v[80:83]
	v_mfma_f32_16x16x32_f16 v[96:99], v[128:131], v[148:151], v[132:135]
	v_mfma_f32_16x16x32_f16 v[80:83], v[128:131], v[156:159], v[56:59]
	s_nop 1
	v_bfe_u32 v132, v169, 2, 4
	v_xor_b32_e32 v56, v168, v169
	v_lshlrev_b32_e32 v56, 4, v56
	v_or_b32_e32 v58, s3, v132
	v_and_b32_e32 v224, 48, v56
	v_ashrrev_i32_e32 v59, 31, v58
	v_lshl_add_u64 v[56:57], s[16:17], 0, v[224:225]
	v_lshlrev_b64 v[58:59], 15, v[58:59]
	v_lshl_add_u64 v[58:59], v[56:57], 0, v[58:59]
	s_lshl_b32 s3, s18, 11
	v_lshl_add_u64 v[58:59], v[58:59], 0, s[46:47]
	s_add_i32 m0, s33, s3
	v_mfma_f32_16x16x32_f16 v[72:75], v[160:163], v[164:167], v[84:87]
	global_load_lds_dwordx4 v[58:59], off
	v_or_b32_e32 v58, s0, v132
	v_lshl_add_u32 v58, s2, 4, v58
	v_ashrrev_i32_e32 v59, 31, v58
	v_lshlrev_b64 v[58:59], 15, v[58:59]
	v_lshl_add_u64 v[56:57], v[56:57], 0, v[58:59]
	s_lshl_b32 s0, s2, 10
	v_lshl_add_u64 v[56:57], v[56:57], 0, s[46:47]
	s_add_i32 m0, s33, s0
	v_mfma_f32_16x16x32_f16 v[84:87], v[48:51], v[156:159], v[68:71]
	global_load_lds_dwordx4 v[56:57], off
	v_add_f32_e32 v132, v122, v123
	v_mfma_f32_16x16x32_f16 v[68:71], v[48:51], v[164:167], v[64:67]
	s_waitcnt vmcnt(0)
	s_waitcnt vmcnt(0) lgkmcnt(0)
	s_barrier
	v_mfma_f32_16x16x32_f16 v[64:67], v[128:131], v[164:167], v[136:139]
	s_and_b32 s0, s18, 3
	v_mfma_f32_16x16x32_f16 v[56:59], v[128:131], v[170:173], v[144:147]
	v_add_f32_e32 v129, v124, v125
	v_add_f32_e32 v131, v126, v127
	v_add_f32_e32 v129, v129, v131
	v_add_f32_e32 v131, v120, v121
	v_add_f32_e32 v129, 0, v129
	v_add_f32_e32 v131, v131, v132
	v_add_f32_e32 v129, v129, v131
	v_add_f32_e32 v131, v116, v117
	v_add_f32_e32 v132, v118, v119
	v_add_f32_e32 v131, v131, v132
	v_add_f32_e32 v129, v129, v131
	v_add_f32_e32 v131, v108, v109
	v_add_f32_e32 v132, v110, v111
	v_add_f32_e32 v131, v131, v132
	v_add_f32_e32 v129, v129, v131
	v_add_f32_e32 v131, v112, v113
	v_add_f32_e32 v132, v114, v115
	v_add_f32_e32 v131, v131, v132
	v_add_f32_e32 v129, v129, v131
	v_add_f32_e32 v131, v104, v105
	v_add_f32_e32 v132, v106, v107
	v_add_f32_e32 v131, v131, v132
	v_add_f32_e32 v129, v129, v131
	v_add_f32_e32 v131, v100, v101
	v_add_f32_e32 v132, v102, v103
	v_add_f32_e32 v131, v131, v132
	v_add_f32_e32 v129, v129, v131
	v_add_f32_e32 v131, v96, v97
	v_add_f32_e32 v132, v98, v99
	v_lshlrev_b32_e32 v130, 2, v169
	v_add_f32_e32 v131, v131, v132
	v_bitop3_b32 v128, v130, 64, v236 bitop3:0x6c
	v_add_f32_e32 v131, v129, v131
	ds_bpermute_b32 v132, v128, v131
	v_bitop3_b32 v130, v130, s1, v236 bitop3:0x6c
	v_mfma_f32_16x16x32_f16 v[88:91], v[160:163], v[156:159], v[88:91]
	v_and_b32_e32 v133, 48, v169
	s_lshl_b32 s0, s0, 2
	s_waitcnt lgkmcnt(0)
	v_add_f32_e32 v131, v131, v132
	ds_bpermute_b32 v132, v130, v131
	v_mfma_f32_16x16x32_f16 v[52:55], v[160:163], v[170:173], v[140:143]
	v_and_b32_e32 v129, 15, v169
	s_ashr_i32 s2, s18, 2
	v_cmp_eq_u32_e32 vcc, 0, v133
	v_mfma_f32_16x16x32_f16 v[48:51], v[48:51], v[170:173], v[152:155]
	s_add_i32 s3, s30, s0
	s_and_saveexec_b64 s[8:9], vcc
	s_cbranch_execz .LBB0_1803
	s_lshl_b32 s7, s2, 10
	s_add_i32 s7, s3, s7
	s_waitcnt lgkmcnt(0)
	v_add_f32_e32 v131, v131, v132
	v_lshl_add_u32 v132, v129, 4, s7
	ds_write_b32 v132, v131
